# removed 17 compiler vmcnt(0) that only drained stores in QKV epilogues / over-waited in GEMM prologues
# speedup vs baseline: 1.0106x; 1.0106x over previous
; #define PG8_STAGE(bufoff, gbase, voff) do { _Pragma("unroll") for (int _i = 0; _i < 2; ++_i) \
;     __builtin_amdgcn_global_load_lds((const unsigned*)((const char*)(gbase) + (voff)[_i]), (LAS unsigned*)(lds + (bufoff) + ldsw + _i * 8192), 16, 0, 0); } while (0)
; #define PG8_WAIT_V(n) asm volatile("s_waitcnt vmcnt(" #n ")" ::: "memory")
; #define PG8_BAR __builtin_amdgcn_s_barrier()
; template <class Epi, class Sched>
; DI void gemm_phase(LAS unsigned char* lds, const Gemm g, const Sched& S, const Epi& E) {
;     ...
;   f32x4 acc[2][2][4][2];
; #pragma unroll
;   for (int a = 0; a < 2; ++a)
; #pragma unroll
;     for (int b = 0; b < 2; ++b)
; #pragma unroll
;       for (int m = 0; m < 4; ++m)
; #pragma unroll
;         for (int n = 0; n < 2; ++n) acc[a][b][m][n] = (f32x4){0.f, 0.f, 0.f, 0.f};
;   bf16x8 At[4][2], B0[2][2], B1[2][2];
;   const char* cA = (const char*)g.A + (size_t)cur.pm * tstep; const char* cB = (const char*)g.Bt + (size_t)cur.pn * tstep;
;   PG8_STAGE(PG8_SB(0, 0), cB, voffB); PG8_STAGE(PG8_SA(0, 0), cA, voffA); PG8_STAGE(PG8_SB(0, 1), cB + hstepB, voffB); PG8_STAGE(PG8_SA(0, 1), cA + hstep, voffA);
;   if (wr == 1) PG8_BAR;
;   PG8_WAIT_V(4); PG8_BAR;
;   PG8_STAGE(PG8_SB(1, 0), cB + kstep, voffB); PG8_STAGE(PG8_SA(1, 0), cA + kstep, voffA); PG8_STAGE(PG8_SB(1, 1), cB + hstepB + kstep, voffB);
;   PG8_WAIT_V(6); PG8_BAR;
.LBB0_135:
	v_lshl_add_u64 v[4:5], s[12:13], 0, v[0:1]
	v_mov_b32_e32 v131, v1
	v_lshl_add_u64 v[6:7], s[12:13], 0, v[130:131]
	v_and_b32_e32 v132, 15, v2
	v_bfe_u32 v136, v2, 4, 2
	s_add_i32 m0, s31, 0x18000
	v_lshl_add_u64 v[2:3], v[4:5], 0, s[70:71]
	v_lshl_add_u64 v[8:9], s[14:15], 0, v[0:1]
	s_waitcnt vmcnt(4)
	s_barrier
	global_load_lds_dwordx4 v[2:3], off
	v_lshl_add_u64 v[2:3], v[6:7], 0, s[70:71]
	s_add_i32 m0, s31, 0x1a000
	s_add_i32 s37, s31, 0x8000
	v_lshl_add_u64 v[10:11], s[14:15], 0, v[130:131]
	global_load_lds_dwordx4 v[2:3], off
	v_lshl_add_u64 v[2:3], v[8:9], 0, s[70:71]
	s_mov_b32 m0, s37
	s_add_i32 s38, s31, 0xa000
	v_lshl_add_u64 v[12:13], s[18:19], 0, v[0:1]
	global_load_lds_dwordx4 v[2:3], off
	v_lshl_add_u64 v[2:3], v[10:11], 0, s[70:71]
	s_mov_b32 m0, s38
	v_lshl_add_u64 v[14:15], s[18:19], 0, v[130:131]
	global_load_lds_dwordx4 v[2:3], off
	s_add_i32 m0, s31, 0x1c000
	v_lshl_add_u64 v[2:3], v[12:13], 0, s[70:71]
	global_load_lds_dwordx4 v[2:3], off
	v_lshl_add_u64 v[2:3], v[14:15], 0, s[70:71]
	s_add_i32 m0, s31, 0x1e000
	s_lshl_b32 s18, s21, 5
	global_load_lds_dwordx4 v[2:3], off
	s_waitcnt vmcnt(6)
	s_and_b32 s27, s18, 0x60
	v_mov_b32_e32 v129, 0
	v_lshl_or_b32 v148, s20, 6, v132
	s_cmp_lt_i32 s16, 64
	v_mov_b32_e32 v128, v129
	v_mov_b32_e32 v127, v129
	v_mov_b32_e32 v126, v129
	v_mov_b32_e32 v125, v129
	v_mov_b32_e32 v124, v129
	v_mov_b32_e32 v123, v129
	v_mov_b32_e32 v122, v129
	v_mov_b32_e32 v113, v129
	v_mov_b32_e32 v112, v129
	v_mov_b32_e32 v111, v129
	v_mov_b32_e32 v110, v129
	v_mov_b32_e32 v109, v129
	v_mov_b32_e32 v108, v129
	v_mov_b32_e32 v107, v129
	v_mov_b32_e32 v106, v129
	v_mov_b32_e32 v97, v129
	v_mov_b32_e32 v96, v129
	v_mov_b32_e32 v95, v129
	v_mov_b32_e32 v94, v129
	v_mov_b32_e32 v93, v129
	v_mov_b32_e32 v92, v129
	v_mov_b32_e32 v91, v129
	v_mov_b32_e32 v90, v129
	v_mov_b32_e32 v81, v129
	v_mov_b32_e32 v80, v129
	v_mov_b32_e32 v79, v129
	v_mov_b32_e32 v78, v129
	v_mov_b32_e32 v77, v129
	v_mov_b32_e32 v76, v129
	v_mov_b32_e32 v75, v129
	v_mov_b32_e32 v74, v129
	v_mov_b32_e32 v121, v129
	v_mov_b32_e32 v120, v129
	v_mov_b32_e32 v119, v129
	v_mov_b32_e32 v118, v129
	v_mov_b32_e32 v117, v129
	v_mov_b32_e32 v116, v129
	v_mov_b32_e32 v115, v129
	v_mov_b32_e32 v114, v129
	v_mov_b32_e32 v105, v129
	v_mov_b32_e32 v104, v129
	v_mov_b32_e32 v103, v129
	v_mov_b32_e32 v102, v129
	v_mov_b32_e32 v101, v129
	v_mov_b32_e32 v100, v129
	v_mov_b32_e32 v99, v129
	v_mov_b32_e32 v98, v129
	v_mov_b32_e32 v89, v129
	v_mov_b32_e32 v88, v129
	v_mov_b32_e32 v87, v129
	v_mov_b32_e32 v86, v129
	v_mov_b32_e32 v85, v129
	v_mov_b32_e32 v84, v129
	v_mov_b32_e32 v83, v129
	v_mov_b32_e32 v82, v129
	v_mov_b32_e32 v73, v129
	v_mov_b32_e32 v72, v129
	v_mov_b32_e32 v71, v129
	v_mov_b32_e32 v70, v129
	v_mov_b32_e32 v69, v129
	v_mov_b32_e32 v68, v129
	v_mov_b32_e32 v67, v129
	v_mov_b32_e32 v66, v129
	v_mov_b32_e32 v65, v129
	v_mov_b32_e32 v64, v129
	v_mov_b32_e32 v63, v129
	v_mov_b32_e32 v62, v129
	v_mov_b32_e32 v61, v129
	v_mov_b32_e32 v60, v129
	v_mov_b32_e32 v59, v129
	v_mov_b32_e32 v58, v129
	v_mov_b32_e32 v49, v129
	v_mov_b32_e32 v48, v129
	v_mov_b32_e32 v47, v129
	v_mov_b32_e32 v46, v129
	v_mov_b32_e32 v45, v129
	v_mov_b32_e32 v44, v129
	v_mov_b32_e32 v43, v129
	v_mov_b32_e32 v42, v129
	v_mov_b32_e32 v33, v129
	v_mov_b32_e32 v32, v129
	v_mov_b32_e32 v31, v129
	v_mov_b32_e32 v30, v129
	v_mov_b32_e32 v29, v129
	v_mov_b32_e32 v28, v129
	v_mov_b32_e32 v27, v129
	v_mov_b32_e32 v26, v129
	v_mov_b32_e32 v17, v129
	v_mov_b32_e32 v16, v129
	v_mov_b32_e32 v15, v129
	v_mov_b32_e32 v14, v129
	v_mov_b32_e32 v13, v129
	v_mov_b32_e32 v12, v129
	v_mov_b32_e32 v11, v129
	v_mov_b32_e32 v10, v129
	v_mov_b32_e32 v57, v129
	v_mov_b32_e32 v56, v129
	v_mov_b32_e32 v55, v129
	v_mov_b32_e32 v54, v129
	v_mov_b32_e32 v53, v129
	v_mov_b32_e32 v52, v129
	v_mov_b32_e32 v51, v129
	v_mov_b32_e32 v50, v129
	v_mov_b32_e32 v41, v129
	v_mov_b32_e32 v40, v129
	v_mov_b32_e32 v39, v129
	v_mov_b32_e32 v38, v129
	v_mov_b32_e32 v37, v129
	v_mov_b32_e32 v36, v129
	v_mov_b32_e32 v35, v129
	v_mov_b32_e32 v34, v129
	v_mov_b32_e32 v25, v129
	v_mov_b32_e32 v24, v129
	v_mov_b32_e32 v23, v129
	v_mov_b32_e32 v22, v129
	v_mov_b32_e32 v21, v129
	v_mov_b32_e32 v20, v129
	v_mov_b32_e32 v19, v129
	v_mov_b32_e32 v18, v129
	v_mov_b32_e32 v9, v129
	v_mov_b32_e32 v8, v129
	v_mov_b32_e32 v7, v129
	v_mov_b32_e32 v6, v129
	v_mov_b32_e32 v5, v129
	v_mov_b32_e32 v4, v129
	v_mov_b32_e32 v3, v129
	v_mov_b32_e32 v2, v129
	s_barrier
; DI int tidx() { int t = threadIdx.x; asm volatile("" : "+v"(t)); return t; }
; template <class Epi, class Sched>
; DI void gemm_phase(LAS unsigned char* lds, const Gemm g, const Sched& S, const Epi& E) {
;   const int tid = tidx(), wid = __builtin_amdgcn_readfirstlane(tid >> 6), lane = tid & 63, wr = wid >> 2, wc = wid & 3, fr = lane & 15, fq = lane >> 4;
;   int K = g.K; asm volatile("" : "+s"(K));
;   const int nt = K / BK;
;   unsigned voffA[2], voffB[2];
; #pragma unroll
;   for (int i = 0; i < 2; ++i) {
;     int R, C; stage_rc(tid * 16 + i * 8192, R, C);
;     int Rb = R;
;     if (Epi::BMAP == 1) Rb = (R & ~31) + perm32(R & 31);
;     if (Epi::BMAP == 2) Rb = 64 * (R >> 5) + perm32(R & 31);
;     voffA[i] = (unsigned)(R * K + C) * 2u; voffB[i] = (unsigned)(Rb * K + C) * 2u;
;   }
;   const size_t kstep = (size_t)(BK * 2);
;   const size_t hstep = (size_t)HALF * K * 2;
;   const size_t hstepB = (Epi::BMAP == 2) ? (size_t)32 * K * 2 : hstep;
;   const size_t tstep = 2 * hstep;
;   const unsigned ldsw = (unsigned)wid * 1024u;
;   const int aoff = lds_byte(wr * 64 + fr, fq * 8), boff = lds_byte(wc * 32 + fr, fq * 8);
;     ...
;   f32x4 acc[2][2][4][2];
; #pragma unroll
;   for (int a = 0; a < 2; ++a)
; #pragma unroll
;     for (int b = 0; b < 2; ++b)
; #pragma unroll
;       for (int m = 0; m < 4; ++m)
; #pragma unroll
;         for (int n = 0; n < 2; ++n) acc[a][b][m][n] = (f32x4){0.f, 0.f, 0.f, 0.f};
	s_cbranch_scc1 .LBB0_138
	s_lshr_b32 s18, s17, 26
	s_add_i32 s18, s16, s18
	s_ashr_i32 s39, s18, 6
	v_lshlrev_b32_e32 v2, 4, v136
	v_lshlrev_b32_e32 v3, 6, v148
	s_movk_i32 s18, 0x3c0
	v_lshlrev_b32_e32 v4, 2, v148
	v_and_or_b32 v3, v3, s18, v2
	s_lshl_b32 s18, s20, 13
	v_and_b32_e32 v4, 32, v4
	v_bitop3_b32 v3, v3, s18, v4 bitop3:0xde
	v_lshlrev_b32_e32 v4, 2, v132
	v_lshl_or_b32 v2, v132, 6, v2
	s_lshl_b32 s18, s27, 7
	v_and_b32_e32 v4, 32, v4
	v_bitop3_b32 v137, v2, s18, v4 bitop3:0xde
	s_lshl_b64 s[18:19], s[0:1], 9
	s_or_b32 s1, s18, 0x100
	s_mul_i32 s17, s1, s17
	s_mul_hi_u32 s18, s1, s16
	s_add_i32 s17, s18, s17
	s_mul_i32 s18, s19, s16
	s_add_i32 s40, s39, -2
	s_add_i32 s17, s17, s18
	s_mul_i32 s1, s1, s16
	s_add_u32 s16, s60, s1
	s_addc_u32 s17, s61, s17
	v_mov_b32_e32 v2, 0
	v_lshl_add_u64 v[132:133], s[16:17], 0, v[0:1]
	v_lshl_add_u64 v[134:135], s[16:17], 0, v[130:131]
	s_mov_b32 s1, 0
	s_mov_b64 s[16:17], 0x80
	v_add_u32_e32 v138, 16, v3
	v_mov_b32_e32 v3, v2
	v_mov_b32_e32 v4, v2
	v_mov_b32_e32 v5, v2
	v_mov_b32_e32 v6, v2
	v_mov_b32_e32 v7, v2
	v_mov_b32_e32 v8, v2
	v_mov_b32_e32 v9, v2
	v_mov_b32_e32 v18, v2
	v_mov_b32_e32 v19, v2
	v_mov_b32_e32 v20, v2
	v_mov_b32_e32 v21, v2
	v_mov_b32_e32 v22, v2
	v_mov_b32_e32 v23, v2
	v_mov_b32_e32 v24, v2
	v_mov_b32_e32 v25, v2
	v_mov_b32_e32 v34, v2
	v_mov_b32_e32 v35, v2
	v_mov_b32_e32 v36, v2
	v_mov_b32_e32 v37, v2
	v_mov_b32_e32 v38, v2
	v_mov_b32_e32 v39, v2
	v_mov_b32_e32 v40, v2
	v_mov_b32_e32 v41, v2
	v_mov_b32_e32 v50, v2
	v_mov_b32_e32 v51, v2
	v_mov_b32_e32 v52, v2
	v_mov_b32_e32 v53, v2
	v_mov_b32_e32 v54, v2
	v_mov_b32_e32 v55, v2
	v_mov_b32_e32 v56, v2
	v_mov_b32_e32 v57, v2
	v_mov_b32_e32 v10, v2
	v_mov_b32_e32 v11, v2
	v_mov_b32_e32 v12, v2
	v_mov_b32_e32 v13, v2
	v_mov_b32_e32 v14, v2
	v_mov_b32_e32 v15, v2
	v_mov_b32_e32 v16, v2
	v_mov_b32_e32 v17, v2
	v_mov_b32_e32 v26, v2
	v_mov_b32_e32 v27, v2
	v_mov_b32_e32 v28, v2
	v_mov_b32_e32 v29, v2
	v_mov_b32_e32 v30, v2
	v_mov_b32_e32 v31, v2
	v_mov_b32_e32 v32, v2
	v_mov_b32_e32 v33, v2
	v_mov_b32_e32 v42, v2
	v_mov_b32_e32 v43, v2
	v_mov_b32_e32 v44, v2
	v_mov_b32_e32 v45, v2
	v_mov_b32_e32 v46, v2
	v_mov_b32_e32 v47, v2
	v_mov_b32_e32 v48, v2
	v_mov_b32_e32 v49, v2
	v_mov_b32_e32 v58, v2
	v_mov_b32_e32 v59, v2
	v_mov_b32_e32 v60, v2
	v_mov_b32_e32 v61, v2
	v_mov_b32_e32 v62, v2
	v_mov_b32_e32 v63, v2
	v_mov_b32_e32 v64, v2
	v_mov_b32_e32 v65, v2
	v_mov_b32_e32 v66, v2
	v_mov_b32_e32 v67, v2
	v_mov_b32_e32 v68, v2
	v_mov_b32_e32 v69, v2
	v_mov_b32_e32 v70, v2
	v_mov_b32_e32 v71, v2
	v_mov_b32_e32 v72, v2
	v_mov_b32_e32 v73, v2
	v_mov_b32_e32 v82, v2
	v_mov_b32_e32 v83, v2
	v_mov_b32_e32 v84, v2
	v_mov_b32_e32 v85, v2
	v_mov_b32_e32 v86, v2
	v_mov_b32_e32 v87, v2
	v_mov_b32_e32 v88, v2
	v_mov_b32_e32 v89, v2
	v_mov_b32_e32 v98, v2
	v_mov_b32_e32 v99, v2
	v_mov_b32_e32 v100, v2
	v_mov_b32_e32 v101, v2
	v_mov_b32_e32 v102, v2
	v_mov_b32_e32 v103, v2
	v_mov_b32_e32 v104, v2
	v_mov_b32_e32 v105, v2
	v_mov_b32_e32 v114, v2
	v_mov_b32_e32 v115, v2
	v_mov_b32_e32 v116, v2
	v_mov_b32_e32 v117, v2
	v_mov_b32_e32 v118, v2
	v_mov_b32_e32 v119, v2
	v_mov_b32_e32 v120, v2
	v_mov_b32_e32 v121, v2
	v_mov_b32_e32 v74, v2
	v_mov_b32_e32 v75, v2
	v_mov_b32_e32 v76, v2
	v_mov_b32_e32 v77, v2
	v_mov_b32_e32 v78, v2
	v_mov_b32_e32 v79, v2
	v_mov_b32_e32 v80, v2
	v_mov_b32_e32 v81, v2
	v_mov_b32_e32 v90, v2
	v_mov_b32_e32 v91, v2
	v_mov_b32_e32 v92, v2
	v_mov_b32_e32 v93, v2
	v_mov_b32_e32 v94, v2
	v_mov_b32_e32 v95, v2
	v_mov_b32_e32 v96, v2
	v_mov_b32_e32 v97, v2
	v_mov_b32_e32 v106, v2
	v_mov_b32_e32 v107, v2
	v_mov_b32_e32 v108, v2
	v_mov_b32_e32 v109, v2
	v_mov_b32_e32 v110, v2
	v_mov_b32_e32 v111, v2
	v_mov_b32_e32 v112, v2
	v_mov_b32_e32 v113, v2
	v_mov_b32_e32 v122, v2
	v_mov_b32_e32 v123, v2
	v_mov_b32_e32 v124, v2
	v_mov_b32_e32 v125, v2
	v_mov_b32_e32 v126, v2
	v_mov_b32_e32 v127, v2
	v_mov_b32_e32 v128, v2
	v_mov_b32_e32 v129, v2

; #define PG8_STAGE(bufoff, gbase, voff) do { _Pragma("unroll") for (int _i = 0; _i < 2; ++_i) \
;     __builtin_amdgcn_global_load_lds((const unsigned*)((const char*)(gbase) + (voff)[_i]), (LAS unsigned*)(lds + (bufoff) + ldsw + _i * 8192), 16, 0, 0); } while (0)
; #define PG8_WAIT_V(n) asm volatile("s_waitcnt vmcnt(" #n ")" ::: "memory")
; #define PG8_BAR __builtin_amdgcn_s_barrier()
; template <class Epi, class Sched>
; DI void gemm_phase(LAS unsigned char* lds, const Gemm g, const Sched& S, const Epi& E) {
;     ...
;   f32x4 acc[2][2][4][2];
; #pragma unroll
;   for (int a = 0; a < 2; ++a)
; #pragma unroll
;     for (int b = 0; b < 2; ++b)
; #pragma unroll
;       for (int m = 0; m < 4; ++m)
; #pragma unroll
;         for (int n = 0; n < 2; ++n) acc[a][b][m][n] = (f32x4){0.f, 0.f, 0.f, 0.f};
;   bf16x8 At[4][2], B0[2][2], B1[2][2];
;   const char* cA = (const char*)g.A + (size_t)cur.pm * tstep; const char* cB = (const char*)g.Bt + (size_t)cur.pn * tstep;
;   PG8_STAGE(PG8_SB(0, 0), cB, voffB); PG8_STAGE(PG8_SA(0, 0), cA, voffA); PG8_STAGE(PG8_SB(0, 1), cB + hstepB, voffB); PG8_STAGE(PG8_SA(0, 1), cA + hstep, voffA);
;   if (wr == 1) PG8_BAR;
;   PG8_WAIT_V(4); PG8_BAR;
;   PG8_STAGE(PG8_SB(1, 0), cB + kstep, voffB); PG8_STAGE(PG8_SA(1, 0), cA + kstep, voffA); PG8_STAGE(PG8_SB(1, 1), cB + hstepB + kstep, voffB);
;   PG8_WAIT_V(6); PG8_BAR;
.LBB0_151:
	v_lshl_add_u64 v[4:5], s[2:3], 0, v[0:1]
	v_mov_b32_e32 v131, v1
	v_lshl_add_u64 v[6:7], s[2:3], 0, v[130:131]
	v_and_b32_e32 v132, 15, v2
	v_bfe_u32 v136, v2, 4, 2
	s_add_i32 m0, s24, 0x18000
	v_lshl_add_u64 v[2:3], v[4:5], 0, s[70:71]
	v_lshl_add_u64 v[8:9], s[12:13], 0, v[0:1]
	s_waitcnt vmcnt(4)
	s_barrier
	global_load_lds_dwordx4 v[2:3], off
	v_lshl_add_u64 v[2:3], v[6:7], 0, s[70:71]
	s_add_i32 m0, s24, 0x1a000
	s_add_i32 s30, s24, 0x8000
	v_lshl_add_u64 v[10:11], s[12:13], 0, v[130:131]
	global_load_lds_dwordx4 v[2:3], off
	v_lshl_add_u64 v[2:3], v[8:9], 0, s[70:71]
	s_mov_b32 m0, s30
	s_add_i32 s31, s24, 0xa000
	v_lshl_add_u64 v[12:13], s[16:17], 0, v[0:1]
	global_load_lds_dwordx4 v[2:3], off
	v_lshl_add_u64 v[2:3], v[10:11], 0, s[70:71]
	s_mov_b32 m0, s31
	v_lshl_add_u64 v[14:15], s[16:17], 0, v[130:131]
	global_load_lds_dwordx4 v[2:3], off
	s_add_i32 m0, s24, 0x1c000
	v_lshl_add_u64 v[2:3], v[12:13], 0, s[70:71]
	global_load_lds_dwordx4 v[2:3], off
	v_lshl_add_u64 v[2:3], v[14:15], 0, s[70:71]
	s_add_i32 m0, s24, 0x1e000
	s_lshl_b32 s16, s19, 5
	global_load_lds_dwordx4 v[2:3], off
	s_waitcnt vmcnt(6)
	s_and_b32 s22, s16, 0x60
	v_mov_b32_e32 v129, 0
	v_lshl_or_b32 v148, s18, 6, v132
	s_cmp_lt_i32 s14, 64
	v_mov_b32_e32 v128, v129
	v_mov_b32_e32 v127, v129
	v_mov_b32_e32 v126, v129
	v_mov_b32_e32 v125, v129
	v_mov_b32_e32 v124, v129
	v_mov_b32_e32 v123, v129
	v_mov_b32_e32 v122, v129
	v_mov_b32_e32 v113, v129
	v_mov_b32_e32 v112, v129
	v_mov_b32_e32 v111, v129
	v_mov_b32_e32 v110, v129
	v_mov_b32_e32 v109, v129
	v_mov_b32_e32 v108, v129
	v_mov_b32_e32 v107, v129
	v_mov_b32_e32 v106, v129
	v_mov_b32_e32 v97, v129
	v_mov_b32_e32 v96, v129
	v_mov_b32_e32 v95, v129
	v_mov_b32_e32 v94, v129
	v_mov_b32_e32 v93, v129
	v_mov_b32_e32 v92, v129
	v_mov_b32_e32 v91, v129
	v_mov_b32_e32 v90, v129
	v_mov_b32_e32 v81, v129
	v_mov_b32_e32 v80, v129
	v_mov_b32_e32 v79, v129
	v_mov_b32_e32 v78, v129
	v_mov_b32_e32 v77, v129
	v_mov_b32_e32 v76, v129
	v_mov_b32_e32 v75, v129
	v_mov_b32_e32 v74, v129
	v_mov_b32_e32 v121, v129
	v_mov_b32_e32 v120, v129
	v_mov_b32_e32 v119, v129
	v_mov_b32_e32 v118, v129
	v_mov_b32_e32 v117, v129
	v_mov_b32_e32 v116, v129
	v_mov_b32_e32 v115, v129
	v_mov_b32_e32 v114, v129
	v_mov_b32_e32 v105, v129
	v_mov_b32_e32 v104, v129
	v_mov_b32_e32 v103, v129
	v_mov_b32_e32 v102, v129
	v_mov_b32_e32 v101, v129
	v_mov_b32_e32 v100, v129
	v_mov_b32_e32 v99, v129
	v_mov_b32_e32 v98, v129
	v_mov_b32_e32 v89, v129
	v_mov_b32_e32 v88, v129
	v_mov_b32_e32 v87, v129
	v_mov_b32_e32 v86, v129
	v_mov_b32_e32 v85, v129
	v_mov_b32_e32 v84, v129
	v_mov_b32_e32 v83, v129
	v_mov_b32_e32 v82, v129
	v_mov_b32_e32 v73, v129
	v_mov_b32_e32 v72, v129
	v_mov_b32_e32 v71, v129
	v_mov_b32_e32 v70, v129
	v_mov_b32_e32 v69, v129
	v_mov_b32_e32 v68, v129
	v_mov_b32_e32 v67, v129
	v_mov_b32_e32 v66, v129
	v_mov_b32_e32 v65, v129
	v_mov_b32_e32 v64, v129
	v_mov_b32_e32 v63, v129
	v_mov_b32_e32 v62, v129
	v_mov_b32_e32 v61, v129
	v_mov_b32_e32 v60, v129
	v_mov_b32_e32 v59, v129
	v_mov_b32_e32 v58, v129
	v_mov_b32_e32 v49, v129
	v_mov_b32_e32 v48, v129
	v_mov_b32_e32 v47, v129
	v_mov_b32_e32 v46, v129
	v_mov_b32_e32 v45, v129
	v_mov_b32_e32 v44, v129
	v_mov_b32_e32 v43, v129
	v_mov_b32_e32 v42, v129
	v_mov_b32_e32 v33, v129
	v_mov_b32_e32 v32, v129
	v_mov_b32_e32 v31, v129
	v_mov_b32_e32 v30, v129
	v_mov_b32_e32 v29, v129
	v_mov_b32_e32 v28, v129
	v_mov_b32_e32 v27, v129
	v_mov_b32_e32 v26, v129
	v_mov_b32_e32 v17, v129
	v_mov_b32_e32 v16, v129
	v_mov_b32_e32 v15, v129
	v_mov_b32_e32 v14, v129
	v_mov_b32_e32 v13, v129
	v_mov_b32_e32 v12, v129
	v_mov_b32_e32 v11, v129
	v_mov_b32_e32 v10, v129
	v_mov_b32_e32 v57, v129
	v_mov_b32_e32 v56, v129
	v_mov_b32_e32 v55, v129
	v_mov_b32_e32 v54, v129
	v_mov_b32_e32 v53, v129
	v_mov_b32_e32 v52, v129
	v_mov_b32_e32 v51, v129
	v_mov_b32_e32 v50, v129
	v_mov_b32_e32 v41, v129
	v_mov_b32_e32 v40, v129
	v_mov_b32_e32 v39, v129
	v_mov_b32_e32 v38, v129
	v_mov_b32_e32 v37, v129
	v_mov_b32_e32 v36, v129
	v_mov_b32_e32 v35, v129
	v_mov_b32_e32 v34, v129
	v_mov_b32_e32 v25, v129
	v_mov_b32_e32 v24, v129
	v_mov_b32_e32 v23, v129
	v_mov_b32_e32 v22, v129
	v_mov_b32_e32 v21, v129
	v_mov_b32_e32 v20, v129
	v_mov_b32_e32 v19, v129
	v_mov_b32_e32 v18, v129
	v_mov_b32_e32 v9, v129
	v_mov_b32_e32 v8, v129
	v_mov_b32_e32 v7, v129
	v_mov_b32_e32 v6, v129
	v_mov_b32_e32 v5, v129
	v_mov_b32_e32 v4, v129
	v_mov_b32_e32 v3, v129
	v_mov_b32_e32 v2, v129
	s_barrier
; DI int tidx() { int t = threadIdx.x; asm volatile("" : "+v"(t)); return t; }
; template <class Epi, class Sched>
; DI void gemm_phase(LAS unsigned char* lds, const Gemm g, const Sched& S, const Epi& E) {
;   const int tid = tidx(), wid = __builtin_amdgcn_readfirstlane(tid >> 6), lane = tid & 63, wr = wid >> 2, wc = wid & 3, fr = lane & 15, fq = lane >> 4;
;   int K = g.K; asm volatile("" : "+s"(K));
;   const int nt = K / BK;
;   unsigned voffA[2], voffB[2];
; #pragma unroll
;   for (int i = 0; i < 2; ++i) {
;     int R, C; stage_rc(tid * 16 + i * 8192, R, C);
;     int Rb = R;
;     if (Epi::BMAP == 1) Rb = (R & ~31) + perm32(R & 31);
;     if (Epi::BMAP == 2) Rb = 64 * (R >> 5) + perm32(R & 31);
;     voffA[i] = (unsigned)(R * K + C) * 2u; voffB[i] = (unsigned)(Rb * K + C) * 2u;
;   }
;   const size_t kstep = (size_t)(BK * 2);
;   const size_t hstep = (size_t)HALF * K * 2;
;   const size_t hstepB = (Epi::BMAP == 2) ? (size_t)32 * K * 2 : hstep;
;   const size_t tstep = 2 * hstep;
;   const unsigned ldsw = (unsigned)wid * 1024u;
;   const int aoff = lds_byte(wr * 64 + fr, fq * 8), boff = lds_byte(wc * 32 + fr, fq * 8);
;     ...
;   f32x4 acc[2][2][4][2];
; #pragma unroll
;   for (int a = 0; a < 2; ++a)
; #pragma unroll
;     for (int b = 0; b < 2; ++b)
; #pragma unroll
;       for (int m = 0; m < 4; ++m)
; #pragma unroll
;         for (int n = 0; n < 2; ++n) acc[a][b][m][n] = (f32x4){0.f, 0.f, 0.f, 0.f};
	s_cbranch_scc1 .LBB0_154
	s_lshr_b32 s15, s15, 26
	s_add_i32 s15, s14, s15
	s_ashr_i32 s34, s15, 6
	v_lshlrev_b32_e32 v2, 4, v136
	v_lshlrev_b32_e32 v3, 6, v148
	s_movk_i32 s15, 0x3c0
	v_lshlrev_b32_e32 v4, 2, v148
	v_and_or_b32 v3, v3, s15, v2
	s_lshl_b32 s15, s18, 13
	v_and_b32_e32 v4, 32, v4
	v_bitop3_b32 v3, v3, s15, v4 bitop3:0xde
	v_lshlrev_b32_e32 v4, 2, v132
	v_lshl_or_b32 v2, v132, 6, v2
	s_lshl_b32 s15, s22, 7
	v_and_b32_e32 v4, 32, v4
	v_readlane_b32 s16, v253, 33
	s_add_i32 s35, s34, -2
	v_bitop3_b32 v137, v2, s15, v4 bitop3:0xde
	s_mul_hi_i32 s15, s16, s14
	s_mul_i32 s14, s16, s14
	s_add_u32 s14, s60, s14
	s_addc_u32 s15, s61, s15
	v_mov_b32_e32 v2, 0
	v_lshl_add_u64 v[132:133], s[14:15], 0, v[0:1]
	v_lshl_add_u64 v[134:135], s[14:15], 0, v[130:131]
	s_mov_b32 s16, 0
	s_mov_b64 s[14:15], 0x5800080
	v_add_u32_e32 v138, 16, v3
	v_mov_b32_e32 v3, v2
	v_mov_b32_e32 v4, v2
	v_mov_b32_e32 v5, v2
	v_mov_b32_e32 v6, v2
	v_mov_b32_e32 v7, v2
	v_mov_b32_e32 v8, v2
	v_mov_b32_e32 v9, v2
	v_mov_b32_e32 v18, v2
	v_mov_b32_e32 v19, v2
	v_mov_b32_e32 v20, v2
	v_mov_b32_e32 v21, v2
	v_mov_b32_e32 v22, v2
	v_mov_b32_e32 v23, v2
	v_mov_b32_e32 v24, v2
	v_mov_b32_e32 v25, v2
	v_mov_b32_e32 v34, v2
	v_mov_b32_e32 v35, v2
	v_mov_b32_e32 v36, v2
	v_mov_b32_e32 v37, v2
	v_mov_b32_e32 v38, v2
	v_mov_b32_e32 v39, v2
	v_mov_b32_e32 v40, v2
	v_mov_b32_e32 v41, v2
	v_mov_b32_e32 v50, v2
	v_mov_b32_e32 v51, v2
	v_mov_b32_e32 v52, v2
	v_mov_b32_e32 v53, v2
	v_mov_b32_e32 v54, v2
	v_mov_b32_e32 v55, v2
	v_mov_b32_e32 v56, v2
	v_mov_b32_e32 v57, v2
	v_mov_b32_e32 v10, v2
	v_mov_b32_e32 v11, v2
	v_mov_b32_e32 v12, v2
	v_mov_b32_e32 v13, v2
	v_mov_b32_e32 v14, v2
	v_mov_b32_e32 v15, v2
	v_mov_b32_e32 v16, v2
	v_mov_b32_e32 v17, v2
	v_mov_b32_e32 v26, v2
	v_mov_b32_e32 v27, v2
	v_mov_b32_e32 v28, v2
	v_mov_b32_e32 v29, v2
	v_mov_b32_e32 v30, v2
	v_mov_b32_e32 v31, v2
	v_mov_b32_e32 v32, v2
	v_mov_b32_e32 v33, v2
	v_mov_b32_e32 v42, v2
	v_mov_b32_e32 v43, v2
	v_mov_b32_e32 v44, v2
	v_mov_b32_e32 v45, v2
	v_mov_b32_e32 v46, v2
	v_mov_b32_e32 v47, v2
	v_mov_b32_e32 v48, v2
	v_mov_b32_e32 v49, v2
	v_mov_b32_e32 v58, v2
	v_mov_b32_e32 v59, v2
	v_mov_b32_e32 v60, v2
	v_mov_b32_e32 v61, v2
	v_mov_b32_e32 v62, v2
	v_mov_b32_e32 v63, v2
	v_mov_b32_e32 v64, v2
	v_mov_b32_e32 v65, v2
	v_mov_b32_e32 v66, v2
	v_mov_b32_e32 v67, v2
	v_mov_b32_e32 v68, v2
	v_mov_b32_e32 v69, v2
	v_mov_b32_e32 v70, v2
	v_mov_b32_e32 v71, v2
	v_mov_b32_e32 v72, v2
	v_mov_b32_e32 v73, v2
	v_mov_b32_e32 v82, v2
	v_mov_b32_e32 v83, v2
	v_mov_b32_e32 v84, v2
	v_mov_b32_e32 v85, v2
	v_mov_b32_e32 v86, v2
	v_mov_b32_e32 v87, v2
	v_mov_b32_e32 v88, v2
	v_mov_b32_e32 v89, v2
	v_mov_b32_e32 v98, v2
	v_mov_b32_e32 v99, v2
	v_mov_b32_e32 v100, v2
	v_mov_b32_e32 v101, v2
	v_mov_b32_e32 v102, v2
	v_mov_b32_e32 v103, v2
	v_mov_b32_e32 v104, v2
	v_mov_b32_e32 v105, v2
	v_mov_b32_e32 v114, v2
	v_mov_b32_e32 v115, v2
	v_mov_b32_e32 v116, v2
	v_mov_b32_e32 v117, v2
	v_mov_b32_e32 v118, v2
	v_mov_b32_e32 v119, v2
	v_mov_b32_e32 v120, v2
	v_mov_b32_e32 v121, v2
	v_mov_b32_e32 v74, v2
	v_mov_b32_e32 v75, v2
	v_mov_b32_e32 v76, v2
	v_mov_b32_e32 v77, v2
	v_mov_b32_e32 v78, v2
	v_mov_b32_e32 v79, v2
	v_mov_b32_e32 v80, v2
	v_mov_b32_e32 v81, v2
	v_mov_b32_e32 v90, v2
	v_mov_b32_e32 v91, v2
	v_mov_b32_e32 v92, v2
	v_mov_b32_e32 v93, v2
	v_mov_b32_e32 v94, v2
	v_mov_b32_e32 v95, v2
	v_mov_b32_e32 v96, v2
	v_mov_b32_e32 v97, v2
	v_mov_b32_e32 v106, v2
	v_mov_b32_e32 v107, v2
	v_mov_b32_e32 v108, v2
	v_mov_b32_e32 v109, v2
	v_mov_b32_e32 v110, v2
	v_mov_b32_e32 v111, v2
	v_mov_b32_e32 v112, v2
	v_mov_b32_e32 v113, v2
	v_mov_b32_e32 v122, v2
	v_mov_b32_e32 v123, v2
	v_mov_b32_e32 v124, v2
	v_mov_b32_e32 v125, v2
	v_mov_b32_e32 v126, v2
	v_mov_b32_e32 v127, v2
	v_mov_b32_e32 v128, v2
	v_mov_b32_e32 v129, v2

; #define PG8_STAGE(bufoff, gbase, voff) do { _Pragma("unroll") for (int _i = 0; _i < 2; ++_i) \
;     __builtin_amdgcn_global_load_lds((const unsigned*)((const char*)(gbase) + (voff)[_i]), (LAS unsigned*)(lds + (bufoff) + ldsw + _i * 8192), 16, 0, 0); } while (0)
; #define PG8_WAIT_V(n) asm volatile("s_waitcnt vmcnt(" #n ")" ::: "memory")
; #define PG8_BAR __builtin_amdgcn_s_barrier()
; template <class Epi, class Sched>
; DI void gemm_phase(LAS unsigned char* lds, const Gemm g, const Sched& S, const Epi& E) {
;     ...
;   f32x4 acc[2][2][4][2];
; #pragma unroll
;   for (int a = 0; a < 2; ++a)
; #pragma unroll
;     for (int b = 0; b < 2; ++b)
; #pragma unroll
;       for (int m = 0; m < 4; ++m)
; #pragma unroll
;         for (int n = 0; n < 2; ++n) acc[a][b][m][n] = (f32x4){0.f, 0.f, 0.f, 0.f};
;   bf16x8 At[4][2], B0[2][2], B1[2][2];
;   const char* cA = (const char*)g.A + (size_t)cur.pm * tstep; const char* cB = (const char*)g.Bt + (size_t)cur.pn * tstep;
;   PG8_STAGE(PG8_SB(0, 0), cB, voffB); PG8_STAGE(PG8_SA(0, 0), cA, voffA); PG8_STAGE(PG8_SB(0, 1), cB + hstepB, voffB); PG8_STAGE(PG8_SA(0, 1), cA + hstep, voffA);
;   if (wr == 1) PG8_BAR;
;   PG8_WAIT_V(4); PG8_BAR;
;   PG8_STAGE(PG8_SB(1, 0), cB + kstep, voffB); PG8_STAGE(PG8_SA(1, 0), cA + kstep, voffA); PG8_STAGE(PG8_SB(1, 1), cB + hstepB + kstep, voffB);
;   PG8_WAIT_V(6); PG8_BAR;
.LBB0_189:
	v_lshl_add_u64 v[4:5], s[2:3], 0, v[0:1]
	v_mov_b32_e32 v131, v1
	v_and_b32_e32 v142, 15, v2
	v_lshrrev_b32_e32 v2, 1, v2
	v_lshl_add_u64 v[6:7], s[2:3], 0, v[130:131]
	v_mov_b32_e32 v135, v1
	v_and_b32_e32 v140, 24, v2
	s_add_i32 m0, s23, 0x18000
	v_lshl_add_u64 v[2:3], v[4:5], 0, s[70:71]
	v_lshl_add_u64 v[8:9], s[12:13], 0, v[134:135]
	v_mov_b32_e32 v133, v1
	s_waitcnt vmcnt(4)
	s_barrier
	global_load_lds_dwordx4 v[2:3], off
	v_lshl_add_u64 v[2:3], v[6:7], 0, s[70:71]
	s_add_i32 m0, s23, 0x1a000
	s_add_i32 s27, s23, 0x8000
	v_lshl_add_u64 v[10:11], s[12:13], 0, v[132:133]
	global_load_lds_dwordx4 v[2:3], off
	v_lshl_add_u64 v[2:3], v[8:9], 0, s[70:71]
	s_mov_b32 m0, s27
	s_add_i32 s29, s23, 0xa000
	v_lshl_add_u64 v[12:13], s[16:17], 0, v[0:1]
	global_load_lds_dwordx4 v[2:3], off
	v_lshl_add_u64 v[2:3], v[10:11], 0, s[70:71]
	s_mov_b32 m0, s29
	v_lshl_add_u64 v[14:15], s[16:17], 0, v[130:131]
	global_load_lds_dwordx4 v[2:3], off
	s_add_i32 m0, s23, 0x1c000
	v_lshl_add_u64 v[2:3], v[12:13], 0, s[70:71]
	global_load_lds_dwordx4 v[2:3], off
	v_lshl_add_u64 v[2:3], v[14:15], 0, s[70:71]
	s_add_i32 m0, s23, 0x1e000
	s_lshl_b32 s16, s19, 5
	global_load_lds_dwordx4 v[2:3], off
	s_waitcnt vmcnt(6)
	s_and_b32 s21, s16, 0x60
	v_mov_b32_e32 v129, 0
	v_lshl_or_b32 v141, s18, 6, v142
	s_cmp_lt_i32 s14, 64
	v_mov_b32_e32 v128, v129
	v_mov_b32_e32 v127, v129
	v_mov_b32_e32 v126, v129
	v_mov_b32_e32 v121, v129
	v_mov_b32_e32 v120, v129
	v_mov_b32_e32 v119, v129
	v_mov_b32_e32 v118, v129
	v_mov_b32_e32 v113, v129
	v_mov_b32_e32 v112, v129
	v_mov_b32_e32 v111, v129
	v_mov_b32_e32 v110, v129
	v_mov_b32_e32 v105, v129
	v_mov_b32_e32 v104, v129
	v_mov_b32_e32 v103, v129
	v_mov_b32_e32 v102, v129
	v_mov_b32_e32 v97, v129
	v_mov_b32_e32 v96, v129
	v_mov_b32_e32 v95, v129
	v_mov_b32_e32 v94, v129
	v_mov_b32_e32 v89, v129
	v_mov_b32_e32 v88, v129
	v_mov_b32_e32 v87, v129
	v_mov_b32_e32 v86, v129
	v_mov_b32_e32 v81, v129
	v_mov_b32_e32 v80, v129
	v_mov_b32_e32 v79, v129
	v_mov_b32_e32 v78, v129
	v_mov_b32_e32 v73, v129
	v_mov_b32_e32 v72, v129
	v_mov_b32_e32 v71, v129
	v_mov_b32_e32 v70, v129
	v_mov_b32_e32 v125, v129
	v_mov_b32_e32 v124, v129
	v_mov_b32_e32 v123, v129
	v_mov_b32_e32 v122, v129
	v_mov_b32_e32 v117, v129
	v_mov_b32_e32 v116, v129
	v_mov_b32_e32 v115, v129
	v_mov_b32_e32 v114, v129
	v_mov_b32_e32 v109, v129
	v_mov_b32_e32 v108, v129
	v_mov_b32_e32 v107, v129
	v_mov_b32_e32 v106, v129
	v_mov_b32_e32 v101, v129
	v_mov_b32_e32 v100, v129
	v_mov_b32_e32 v99, v129
	v_mov_b32_e32 v98, v129
	v_mov_b32_e32 v93, v129
	v_mov_b32_e32 v92, v129
	v_mov_b32_e32 v91, v129
	v_mov_b32_e32 v90, v129
	v_mov_b32_e32 v85, v129
	v_mov_b32_e32 v84, v129
	v_mov_b32_e32 v83, v129
	v_mov_b32_e32 v82, v129
	v_mov_b32_e32 v77, v129
	v_mov_b32_e32 v76, v129
	v_mov_b32_e32 v75, v129
	v_mov_b32_e32 v74, v129
	v_mov_b32_e32 v69, v129
	v_mov_b32_e32 v68, v129
	v_mov_b32_e32 v67, v129
	v_mov_b32_e32 v66, v129
	v_mov_b32_e32 v65, v129
	v_mov_b32_e32 v64, v129
	v_mov_b32_e32 v63, v129
	v_mov_b32_e32 v62, v129
	v_mov_b32_e32 v57, v129
	v_mov_b32_e32 v56, v129
	v_mov_b32_e32 v55, v129
	v_mov_b32_e32 v54, v129
	v_mov_b32_e32 v49, v129
	v_mov_b32_e32 v48, v129
	v_mov_b32_e32 v47, v129
	v_mov_b32_e32 v46, v129
	v_mov_b32_e32 v41, v129
	v_mov_b32_e32 v40, v129
	v_mov_b32_e32 v39, v129
	v_mov_b32_e32 v38, v129
	v_mov_b32_e32 v33, v129
	v_mov_b32_e32 v32, v129
	v_mov_b32_e32 v31, v129
	v_mov_b32_e32 v30, v129
	v_mov_b32_e32 v25, v129
	v_mov_b32_e32 v24, v129
	v_mov_b32_e32 v23, v129
	v_mov_b32_e32 v22, v129
	v_mov_b32_e32 v17, v129
	v_mov_b32_e32 v16, v129
	v_mov_b32_e32 v15, v129
	v_mov_b32_e32 v14, v129
	v_mov_b32_e32 v9, v129
	v_mov_b32_e32 v8, v129
	v_mov_b32_e32 v7, v129
	v_mov_b32_e32 v6, v129
	v_mov_b32_e32 v61, v129
	v_mov_b32_e32 v60, v129
	v_mov_b32_e32 v59, v129
	v_mov_b32_e32 v58, v129
	v_mov_b32_e32 v53, v129
	v_mov_b32_e32 v52, v129
	v_mov_b32_e32 v51, v129
	v_mov_b32_e32 v50, v129
	v_mov_b32_e32 v45, v129
	v_mov_b32_e32 v44, v129
	v_mov_b32_e32 v43, v129
	v_mov_b32_e32 v42, v129
	v_mov_b32_e32 v37, v129
	v_mov_b32_e32 v36, v129
	v_mov_b32_e32 v35, v129
	v_mov_b32_e32 v34, v129
	v_mov_b32_e32 v29, v129
	v_mov_b32_e32 v28, v129
	v_mov_b32_e32 v27, v129
	v_mov_b32_e32 v26, v129
	v_mov_b32_e32 v21, v129
	v_mov_b32_e32 v20, v129
	v_mov_b32_e32 v19, v129
	v_mov_b32_e32 v18, v129
	v_mov_b32_e32 v13, v129
	v_mov_b32_e32 v12, v129
	v_mov_b32_e32 v11, v129
	v_mov_b32_e32 v10, v129
	v_mov_b32_e32 v5, v129
	v_mov_b32_e32 v4, v129
	v_mov_b32_e32 v3, v129
	v_mov_b32_e32 v2, v129
	s_barrier
; DI int tidx() { int t = threadIdx.x; asm volatile("" : "+v"(t)); return t; }
; template <class Epi, class Sched>
; DI void gemm_phase(LAS unsigned char* lds, const Gemm g, const Sched& S, const Epi& E) {
;   const int tid = tidx(), wid = __builtin_amdgcn_readfirstlane(tid >> 6), lane = tid & 63, wr = wid >> 2, wc = wid & 3, fr = lane & 15, fq = lane >> 4;
;   int K = g.K; asm volatile("" : "+s"(K));
;   const int nt = K / BK;
;   unsigned voffA[2], voffB[2];
; #pragma unroll
;   for (int i = 0; i < 2; ++i) {
;     int R, C; stage_rc(tid * 16 + i * 8192, R, C);
;     int Rb = R;
;     if (Epi::BMAP == 1) Rb = (R & ~31) + perm32(R & 31);
;     if (Epi::BMAP == 2) Rb = 64 * (R >> 5) + perm32(R & 31);
;     voffA[i] = (unsigned)(R * K + C) * 2u; voffB[i] = (unsigned)(Rb * K + C) * 2u;
;   }
;   const size_t kstep = (size_t)(BK * 2);
;   const size_t hstep = (size_t)HALF * K * 2;
;   const size_t hstepB = (Epi::BMAP == 2) ? (size_t)32 * K * 2 : hstep;
;   const size_t tstep = 2 * hstep;
;   const unsigned ldsw = (unsigned)wid * 1024u;
;   const int aoff = lds_byte(wr * 64 + fr, fq * 8), boff = lds_byte(wc * 32 + fr, fq * 8);
;     ...
;   f32x4 acc[2][2][4][2];
; #pragma unroll
;   for (int a = 0; a < 2; ++a)
; #pragma unroll
;     for (int b = 0; b < 2; ++b)
; #pragma unroll
;       for (int m = 0; m < 4; ++m)
; #pragma unroll
;         for (int n = 0; n < 2; ++n) acc[a][b][m][n] = (f32x4){0.f, 0.f, 0.f, 0.f};
	s_cbranch_scc1 .LBB0_192
	s_lshr_b32 s15, s15, 26
	s_add_i32 s15, s14, s15
	s_ashr_i32 s30, s15, 6
	v_lshlrev_b32_e32 v2, 6, v141
	v_lshlrev_b32_e32 v3, 1, v140
	s_movk_i32 s15, 0x3c0
	v_lshlrev_b32_e32 v4, 2, v141
	v_and_or_b32 v2, v2, s15, v3
	s_lshl_b32 s15, s18, 13
	v_and_b32_e32 v4, 32, v4
	v_bitop3_b32 v4, v2, s15, v4 bitop3:0xde
	v_lshl_or_b32 v2, v142, 6, v3
	v_lshlrev_b32_e32 v3, 2, v142
	s_lshl_b32 s15, s21, 7
	v_and_b32_e32 v3, 32, v3
	v_readlane_b32 s16, v253, 35
	s_add_i32 s31, s30, -2
	v_bitop3_b32 v142, v2, s15, v3 bitop3:0xde
	s_mul_hi_i32 s15, s16, s14
	s_mul_i32 s14, s16, s14
	v_add_u32_e32 v2, v144, v136
	s_add_u32 s14, s86, s14
	v_add_lshl_u32 v2, v2, v137, 1
	v_mov_b32_e32 v3, v1
	s_addc_u32 s15, s87, s15
	v_lshl_add_u64 v[136:137], s[14:15], 0, v[2:3]
	v_add_u32_e32 v2, v143, v138
	v_add_lshl_u32 v2, v2, v139, 1
	v_lshl_add_u64 v[138:139], s[14:15], 0, v[2:3]
	v_mov_b32_e32 v2, 0
	s_mov_b32 s16, 0
	s_mov_b64 s[14:15], 0x2000080
	v_add_u32_e32 v143, 16, v4
	v_mov_b32_e32 v3, v2
	v_mov_b32_e32 v4, v2
	v_mov_b32_e32 v5, v2
	v_mov_b32_e32 v10, v2
	v_mov_b32_e32 v11, v2
	v_mov_b32_e32 v12, v2
	v_mov_b32_e32 v13, v2
	v_mov_b32_e32 v18, v2
	v_mov_b32_e32 v19, v2
	v_mov_b32_e32 v20, v2
	v_mov_b32_e32 v21, v2
	v_mov_b32_e32 v26, v2
	v_mov_b32_e32 v27, v2
	v_mov_b32_e32 v28, v2
	v_mov_b32_e32 v29, v2
	v_mov_b32_e32 v34, v2
	v_mov_b32_e32 v35, v2
	v_mov_b32_e32 v36, v2
	v_mov_b32_e32 v37, v2
	v_mov_b32_e32 v42, v2
	v_mov_b32_e32 v43, v2
	v_mov_b32_e32 v44, v2
	v_mov_b32_e32 v45, v2
	v_mov_b32_e32 v50, v2
	v_mov_b32_e32 v51, v2
	v_mov_b32_e32 v52, v2
	v_mov_b32_e32 v53, v2
	v_mov_b32_e32 v58, v2
	v_mov_b32_e32 v59, v2
	v_mov_b32_e32 v60, v2
	v_mov_b32_e32 v61, v2
	v_mov_b32_e32 v6, v2
	v_mov_b32_e32 v7, v2
	v_mov_b32_e32 v8, v2
	v_mov_b32_e32 v9, v2
	v_mov_b32_e32 v14, v2
	v_mov_b32_e32 v15, v2
	v_mov_b32_e32 v16, v2
	v_mov_b32_e32 v17, v2
	v_mov_b32_e32 v22, v2
	v_mov_b32_e32 v23, v2
	v_mov_b32_e32 v24, v2
	v_mov_b32_e32 v25, v2
	v_mov_b32_e32 v30, v2
	v_mov_b32_e32 v31, v2
	v_mov_b32_e32 v32, v2
	v_mov_b32_e32 v33, v2
	v_mov_b32_e32 v38, v2
	v_mov_b32_e32 v39, v2
	v_mov_b32_e32 v40, v2
	v_mov_b32_e32 v41, v2
	v_mov_b32_e32 v46, v2
	v_mov_b32_e32 v47, v2
	v_mov_b32_e32 v48, v2
	v_mov_b32_e32 v49, v2
	v_mov_b32_e32 v54, v2
	v_mov_b32_e32 v55, v2
	v_mov_b32_e32 v56, v2
	v_mov_b32_e32 v57, v2
	v_mov_b32_e32 v62, v2
	v_mov_b32_e32 v63, v2
	v_mov_b32_e32 v64, v2
	v_mov_b32_e32 v65, v2
	v_mov_b32_e32 v66, v2
	v_mov_b32_e32 v67, v2
	v_mov_b32_e32 v68, v2
	v_mov_b32_e32 v69, v2
	v_mov_b32_e32 v74, v2
	v_mov_b32_e32 v75, v2
	v_mov_b32_e32 v76, v2
	v_mov_b32_e32 v77, v2
	v_mov_b32_e32 v82, v2
	v_mov_b32_e32 v83, v2
	v_mov_b32_e32 v84, v2
	v_mov_b32_e32 v85, v2
	v_mov_b32_e32 v90, v2
	v_mov_b32_e32 v91, v2
	v_mov_b32_e32 v92, v2
	v_mov_b32_e32 v93, v2
	v_mov_b32_e32 v98, v2
	v_mov_b32_e32 v99, v2
	v_mov_b32_e32 v100, v2
	v_mov_b32_e32 v101, v2
	v_mov_b32_e32 v106, v2
	v_mov_b32_e32 v107, v2
	v_mov_b32_e32 v108, v2
	v_mov_b32_e32 v109, v2
	v_mov_b32_e32 v114, v2
	v_mov_b32_e32 v115, v2
	v_mov_b32_e32 v116, v2
	v_mov_b32_e32 v117, v2
	v_mov_b32_e32 v122, v2
	v_mov_b32_e32 v123, v2
	v_mov_b32_e32 v124, v2
	v_mov_b32_e32 v125, v2
	v_mov_b32_e32 v70, v2
	v_mov_b32_e32 v71, v2
	v_mov_b32_e32 v72, v2
	v_mov_b32_e32 v73, v2
	v_mov_b32_e32 v78, v2
	v_mov_b32_e32 v79, v2
	v_mov_b32_e32 v80, v2
	v_mov_b32_e32 v81, v2
	v_mov_b32_e32 v86, v2
	v_mov_b32_e32 v87, v2
	v_mov_b32_e32 v88, v2
	v_mov_b32_e32 v89, v2
	v_mov_b32_e32 v94, v2
	v_mov_b32_e32 v95, v2
	v_mov_b32_e32 v96, v2
	v_mov_b32_e32 v97, v2
	v_mov_b32_e32 v102, v2
	v_mov_b32_e32 v103, v2
	v_mov_b32_e32 v104, v2
	v_mov_b32_e32 v105, v2
	v_mov_b32_e32 v110, v2
	v_mov_b32_e32 v111, v2
	v_mov_b32_e32 v112, v2
	v_mov_b32_e32 v113, v2
	v_mov_b32_e32 v118, v2
	v_mov_b32_e32 v119, v2
	v_mov_b32_e32 v120, v2
	v_mov_b32_e32 v121, v2
	v_mov_b32_e32 v126, v2
	v_mov_b32_e32 v127, v2
	v_mov_b32_e32 v128, v2
	v_mov_b32_e32 v129, v2

; #define PG8_STAGE(bufoff, gbase, voff) do { _Pragma("unroll") for (int _i = 0; _i < 2; ++_i) \
;     __builtin_amdgcn_global_load_lds((const unsigned*)((const char*)(gbase) + (voff)[_i]), (LAS unsigned*)(lds + (bufoff) + ldsw + _i * 8192), 16, 0, 0); } while (0)
; #define PG8_WAIT_V(n) asm volatile("s_waitcnt vmcnt(" #n ")" ::: "memory")
; #define PG8_BAR __builtin_amdgcn_s_barrier()
; template <class Epi, class Sched>
; DI void gemm_phase(LAS unsigned char* lds, const Gemm g, const Sched& S, const Epi& E) {
;     ...
;   f32x4 acc[2][2][4][2];
; #pragma unroll
;   for (int a = 0; a < 2; ++a)
; #pragma unroll
;     for (int b = 0; b < 2; ++b)
; #pragma unroll
;       for (int m = 0; m < 4; ++m)
; #pragma unroll
;         for (int n = 0; n < 2; ++n) acc[a][b][m][n] = (f32x4){0.f, 0.f, 0.f, 0.f};
;   bf16x8 At[4][2], B0[2][2], B1[2][2];
;   const char* cA = (const char*)g.A + (size_t)cur.pm * tstep; const char* cB = (const char*)g.Bt + (size_t)cur.pn * tstep;
;   PG8_STAGE(PG8_SB(0, 0), cB, voffB); PG8_STAGE(PG8_SA(0, 0), cA, voffA); PG8_STAGE(PG8_SB(0, 1), cB + hstepB, voffB); PG8_STAGE(PG8_SA(0, 1), cA + hstep, voffA);
;   if (wr == 1) PG8_BAR;
;   PG8_WAIT_V(4); PG8_BAR;
;   PG8_STAGE(PG8_SB(1, 0), cB + kstep, voffB); PG8_STAGE(PG8_SA(1, 0), cA + kstep, voffA); PG8_STAGE(PG8_SB(1, 1), cB + hstepB + kstep, voffB);
;   PG8_WAIT_V(6); PG8_BAR;
.LBB0_215:
	v_lshl_add_u64 v[4:5], s[12:13], 0, v[0:1]
	v_mov_b32_e32 v131, v1
	v_lshl_add_u64 v[6:7], s[12:13], 0, v[130:131]
	v_and_b32_e32 v132, 15, v2
	v_bfe_u32 v136, v2, 4, 2
	s_add_i32 m0, s30, 0x18000
	v_lshl_add_u64 v[2:3], v[4:5], 0, s[70:71]
	v_lshl_add_u64 v[8:9], s[14:15], 0, v[0:1]
	s_waitcnt vmcnt(4)
	s_barrier
	global_load_lds_dwordx4 v[2:3], off
	v_lshl_add_u64 v[2:3], v[6:7], 0, s[70:71]
	s_add_i32 m0, s30, 0x1a000
	s_add_i32 s36, s30, 0x8000
	v_lshl_add_u64 v[10:11], s[14:15], 0, v[130:131]
	global_load_lds_dwordx4 v[2:3], off
	v_lshl_add_u64 v[2:3], v[8:9], 0, s[70:71]
	s_mov_b32 m0, s36
	s_add_i32 s37, s30, 0xa000
	v_lshl_add_u64 v[12:13], s[18:19], 0, v[0:1]
	global_load_lds_dwordx4 v[2:3], off
	v_lshl_add_u64 v[2:3], v[10:11], 0, s[70:71]
	s_mov_b32 m0, s37
	v_lshl_add_u64 v[14:15], s[18:19], 0, v[130:131]
	global_load_lds_dwordx4 v[2:3], off
	s_add_i32 m0, s30, 0x1c000
	v_lshl_add_u64 v[2:3], v[12:13], 0, s[70:71]
	global_load_lds_dwordx4 v[2:3], off
	v_lshl_add_u64 v[2:3], v[14:15], 0, s[70:71]
	s_add_i32 m0, s30, 0x1e000
	s_lshl_b32 s18, s21, 5
	global_load_lds_dwordx4 v[2:3], off
	s_waitcnt vmcnt(6)
	s_and_b32 s27, s18, 0x60
	v_mov_b32_e32 v129, 0
	v_lshl_or_b32 v146, s20, 6, v132
	s_cmp_lt_i32 s16, 64
	v_mov_b32_e32 v128, v129
	v_mov_b32_e32 v127, v129
	v_mov_b32_e32 v126, v129
	v_mov_b32_e32 v125, v129
	v_mov_b32_e32 v124, v129
	v_mov_b32_e32 v123, v129
	v_mov_b32_e32 v122, v129
	v_mov_b32_e32 v113, v129
	v_mov_b32_e32 v112, v129
	v_mov_b32_e32 v111, v129
	v_mov_b32_e32 v110, v129
	v_mov_b32_e32 v109, v129
	v_mov_b32_e32 v108, v129
	v_mov_b32_e32 v107, v129
	v_mov_b32_e32 v106, v129
	v_mov_b32_e32 v97, v129
	v_mov_b32_e32 v96, v129
	v_mov_b32_e32 v95, v129
	v_mov_b32_e32 v94, v129
	v_mov_b32_e32 v93, v129
	v_mov_b32_e32 v92, v129
	v_mov_b32_e32 v91, v129
	v_mov_b32_e32 v90, v129
	v_mov_b32_e32 v81, v129
	v_mov_b32_e32 v80, v129
	v_mov_b32_e32 v79, v129
	v_mov_b32_e32 v78, v129
	v_mov_b32_e32 v77, v129
	v_mov_b32_e32 v76, v129
	v_mov_b32_e32 v75, v129
	v_mov_b32_e32 v74, v129
	v_mov_b32_e32 v121, v129
	v_mov_b32_e32 v120, v129
	v_mov_b32_e32 v119, v129
	v_mov_b32_e32 v118, v129
	v_mov_b32_e32 v117, v129
	v_mov_b32_e32 v116, v129
	v_mov_b32_e32 v115, v129
	v_mov_b32_e32 v114, v129
	v_mov_b32_e32 v105, v129
	v_mov_b32_e32 v104, v129
	v_mov_b32_e32 v103, v129
	v_mov_b32_e32 v102, v129
	v_mov_b32_e32 v101, v129
	v_mov_b32_e32 v100, v129
	v_mov_b32_e32 v99, v129
	v_mov_b32_e32 v98, v129
	v_mov_b32_e32 v89, v129
	v_mov_b32_e32 v88, v129
	v_mov_b32_e32 v87, v129
	v_mov_b32_e32 v86, v129
	v_mov_b32_e32 v85, v129
	v_mov_b32_e32 v84, v129
	v_mov_b32_e32 v83, v129
	v_mov_b32_e32 v82, v129
	v_mov_b32_e32 v73, v129
	v_mov_b32_e32 v72, v129
	v_mov_b32_e32 v71, v129
	v_mov_b32_e32 v70, v129
	v_mov_b32_e32 v69, v129
	v_mov_b32_e32 v68, v129
	v_mov_b32_e32 v67, v129
	v_mov_b32_e32 v66, v129
	v_mov_b32_e32 v65, v129
	v_mov_b32_e32 v64, v129
	v_mov_b32_e32 v63, v129
	v_mov_b32_e32 v62, v129
	v_mov_b32_e32 v61, v129
	v_mov_b32_e32 v60, v129
	v_mov_b32_e32 v59, v129
	v_mov_b32_e32 v58, v129
	v_mov_b32_e32 v53, v129
	v_mov_b32_e32 v52, v129
	v_mov_b32_e32 v51, v129
	v_mov_b32_e32 v50, v129
	v_mov_b32_e32 v45, v129
	v_mov_b32_e32 v44, v129
	v_mov_b32_e32 v43, v129
	v_mov_b32_e32 v42, v129
	v_mov_b32_e32 v37, v129
	v_mov_b32_e32 v36, v129
	v_mov_b32_e32 v35, v129
	v_mov_b32_e32 v34, v129
	v_mov_b32_e32 v29, v129
	v_mov_b32_e32 v28, v129
	v_mov_b32_e32 v27, v129
	v_mov_b32_e32 v26, v129
	v_mov_b32_e32 v17, v129
	v_mov_b32_e32 v16, v129
	v_mov_b32_e32 v15, v129
	v_mov_b32_e32 v14, v129
	v_mov_b32_e32 v13, v129
	v_mov_b32_e32 v12, v129
	v_mov_b32_e32 v11, v129
	v_mov_b32_e32 v10, v129
	v_mov_b32_e32 v57, v129
	v_mov_b32_e32 v56, v129
	v_mov_b32_e32 v55, v129
	v_mov_b32_e32 v54, v129
	v_mov_b32_e32 v49, v129
	v_mov_b32_e32 v48, v129
	v_mov_b32_e32 v47, v129
	v_mov_b32_e32 v46, v129
	v_mov_b32_e32 v41, v129
	v_mov_b32_e32 v40, v129
	v_mov_b32_e32 v39, v129
	v_mov_b32_e32 v38, v129
	v_mov_b32_e32 v33, v129
	v_mov_b32_e32 v32, v129
	v_mov_b32_e32 v31, v129
	v_mov_b32_e32 v30, v129
	v_mov_b32_e32 v25, v129
	v_mov_b32_e32 v24, v129
	v_mov_b32_e32 v23, v129
	v_mov_b32_e32 v22, v129
	v_mov_b32_e32 v21, v129
	v_mov_b32_e32 v20, v129
	v_mov_b32_e32 v19, v129
	v_mov_b32_e32 v18, v129
	v_mov_b32_e32 v9, v129
	v_mov_b32_e32 v8, v129
	v_mov_b32_e32 v7, v129
	v_mov_b32_e32 v6, v129
	v_mov_b32_e32 v5, v129
	v_mov_b32_e32 v4, v129
	v_mov_b32_e32 v3, v129
	v_mov_b32_e32 v2, v129
	s_barrier
; DI int tidx() { int t = threadIdx.x; asm volatile("" : "+v"(t)); return t; }
; template <class Epi, class Sched>
; DI void gemm_phase(LAS unsigned char* lds, const Gemm g, const Sched& S, const Epi& E) {
;   const int tid = tidx(), wid = __builtin_amdgcn_readfirstlane(tid >> 6), lane = tid & 63, wr = wid >> 2, wc = wid & 3, fr = lane & 15, fq = lane >> 4;
;   int K = g.K; asm volatile("" : "+s"(K));
;   const int nt = K / BK;
;   unsigned voffA[2], voffB[2];
; #pragma unroll
;   for (int i = 0; i < 2; ++i) {
;     int R, C; stage_rc(tid * 16 + i * 8192, R, C);
;     int Rb = R;
;     if (Epi::BMAP == 1) Rb = (R & ~31) + perm32(R & 31);
;     if (Epi::BMAP == 2) Rb = 64 * (R >> 5) + perm32(R & 31);
;     voffA[i] = (unsigned)(R * K + C) * 2u; voffB[i] = (unsigned)(Rb * K + C) * 2u;
;   }
;   const size_t kstep = (size_t)(BK * 2);
;   const size_t hstep = (size_t)HALF * K * 2;
;   const size_t hstepB = (Epi::BMAP == 2) ? (size_t)32 * K * 2 : hstep;
;   const size_t tstep = 2 * hstep;
;   const unsigned ldsw = (unsigned)wid * 1024u;
;   const int aoff = lds_byte(wr * 64 + fr, fq * 8), boff = lds_byte(wc * 32 + fr, fq * 8);
;     ...
;   f32x4 acc[2][2][4][2];
; #pragma unroll
;   for (int a = 0; a < 2; ++a)
; #pragma unroll
;     for (int b = 0; b < 2; ++b)
; #pragma unroll
;       for (int m = 0; m < 4; ++m)
; #pragma unroll
;         for (int n = 0; n < 2; ++n) acc[a][b][m][n] = (f32x4){0.f, 0.f, 0.f, 0.f};
	s_cbranch_scc1 .LBB0_218
	s_lshr_b32 s18, s17, 26
	s_add_i32 s18, s16, s18
	s_ashr_i32 s38, s18, 6
	v_lshlrev_b32_e32 v2, 4, v136
	v_lshlrev_b32_e32 v3, 6, v146
	s_movk_i32 s18, 0x3c0
	v_lshlrev_b32_e32 v4, 2, v146
	v_and_or_b32 v3, v3, s18, v2
	s_lshl_b32 s18, s20, 13
	v_and_b32_e32 v4, 32, v4
	v_bitop3_b32 v3, v3, s18, v4 bitop3:0xde
	v_lshlrev_b32_e32 v4, 2, v132
	v_lshl_or_b32 v2, v132, 6, v2
	s_lshl_b32 s18, s27, 7
	v_and_b32_e32 v4, 32, v4
	v_bitop3_b32 v137, v2, s18, v4 bitop3:0xde
	s_lshl_b64 s[18:19], s[2:3], 9
	s_or_b32 s3, s18, 0x100
	s_mul_i32 s17, s3, s17
	s_mul_hi_u32 s18, s3, s16
	s_add_i32 s17, s18, s17
	s_mul_i32 s18, s19, s16
	s_add_i32 s39, s38, -2
	s_add_i32 s17, s17, s18
	s_mul_i32 s3, s3, s16
	s_add_u32 s16, s90, s3
	s_addc_u32 s17, s91, s17
	v_mov_b32_e32 v2, 0
	v_lshl_add_u64 v[132:133], s[16:17], 0, v[0:1]
	v_lshl_add_u64 v[134:135], s[16:17], 0, v[130:131]
	s_mov_b32 s3, 0
	s_mov_b64 s[16:17], 0x80
	v_add_u32_e32 v138, 16, v3
	v_mov_b32_e32 v3, v2
	v_mov_b32_e32 v4, v2
	v_mov_b32_e32 v5, v2
	v_mov_b32_e32 v6, v2
	v_mov_b32_e32 v7, v2
	v_mov_b32_e32 v8, v2
	v_mov_b32_e32 v9, v2
	v_mov_b32_e32 v18, v2
	v_mov_b32_e32 v19, v2
	v_mov_b32_e32 v20, v2
	v_mov_b32_e32 v21, v2
	v_mov_b32_e32 v22, v2
	v_mov_b32_e32 v23, v2
	v_mov_b32_e32 v24, v2
	v_mov_b32_e32 v25, v2
	v_mov_b32_e32 v30, v2
	v_mov_b32_e32 v31, v2
	v_mov_b32_e32 v32, v2
	v_mov_b32_e32 v33, v2
	v_mov_b32_e32 v38, v2
	v_mov_b32_e32 v39, v2
	v_mov_b32_e32 v40, v2
	v_mov_b32_e32 v41, v2
	v_mov_b32_e32 v46, v2
	v_mov_b32_e32 v47, v2
	v_mov_b32_e32 v48, v2
	v_mov_b32_e32 v49, v2
	v_mov_b32_e32 v54, v2
	v_mov_b32_e32 v55, v2
	v_mov_b32_e32 v56, v2
	v_mov_b32_e32 v57, v2
	v_mov_b32_e32 v10, v2
	v_mov_b32_e32 v11, v2
	v_mov_b32_e32 v12, v2
	v_mov_b32_e32 v13, v2
	v_mov_b32_e32 v14, v2
	v_mov_b32_e32 v15, v2
	v_mov_b32_e32 v16, v2
	v_mov_b32_e32 v17, v2
	v_mov_b32_e32 v26, v2
	v_mov_b32_e32 v27, v2
	v_mov_b32_e32 v28, v2
	v_mov_b32_e32 v29, v2
	v_mov_b32_e32 v34, v2
	v_mov_b32_e32 v35, v2
	v_mov_b32_e32 v36, v2
	v_mov_b32_e32 v37, v2
	v_mov_b32_e32 v42, v2
	v_mov_b32_e32 v43, v2
	v_mov_b32_e32 v44, v2
	v_mov_b32_e32 v45, v2
	v_mov_b32_e32 v50, v2
	v_mov_b32_e32 v51, v2
	v_mov_b32_e32 v52, v2
	v_mov_b32_e32 v53, v2
	v_mov_b32_e32 v58, v2
	v_mov_b32_e32 v59, v2
	v_mov_b32_e32 v60, v2
	v_mov_b32_e32 v61, v2
	v_mov_b32_e32 v62, v2
	v_mov_b32_e32 v63, v2
	v_mov_b32_e32 v64, v2
	v_mov_b32_e32 v65, v2
	v_mov_b32_e32 v66, v2
	v_mov_b32_e32 v67, v2
	v_mov_b32_e32 v68, v2
	v_mov_b32_e32 v69, v2
	v_mov_b32_e32 v70, v2
	v_mov_b32_e32 v71, v2
	v_mov_b32_e32 v72, v2
	v_mov_b32_e32 v73, v2
	v_mov_b32_e32 v82, v2
	v_mov_b32_e32 v83, v2
	v_mov_b32_e32 v84, v2
	v_mov_b32_e32 v85, v2
	v_mov_b32_e32 v86, v2
	v_mov_b32_e32 v87, v2
	v_mov_b32_e32 v88, v2
	v_mov_b32_e32 v89, v2
	v_mov_b32_e32 v98, v2
	v_mov_b32_e32 v99, v2
	v_mov_b32_e32 v100, v2
	v_mov_b32_e32 v101, v2
	v_mov_b32_e32 v102, v2
	v_mov_b32_e32 v103, v2
	v_mov_b32_e32 v104, v2
	v_mov_b32_e32 v105, v2
	v_mov_b32_e32 v114, v2
	v_mov_b32_e32 v115, v2
	v_mov_b32_e32 v116, v2
	v_mov_b32_e32 v117, v2
	v_mov_b32_e32 v118, v2
	v_mov_b32_e32 v119, v2
	v_mov_b32_e32 v120, v2
	v_mov_b32_e32 v121, v2
	v_mov_b32_e32 v74, v2
	v_mov_b32_e32 v75, v2
	v_mov_b32_e32 v76, v2
	v_mov_b32_e32 v77, v2
	v_mov_b32_e32 v78, v2
	v_mov_b32_e32 v79, v2
	v_mov_b32_e32 v80, v2
	v_mov_b32_e32 v81, v2
	v_mov_b32_e32 v90, v2
	v_mov_b32_e32 v91, v2
	v_mov_b32_e32 v92, v2
	v_mov_b32_e32 v93, v2
	v_mov_b32_e32 v94, v2
	v_mov_b32_e32 v95, v2
	v_mov_b32_e32 v96, v2
	v_mov_b32_e32 v97, v2
	v_mov_b32_e32 v106, v2
	v_mov_b32_e32 v107, v2
	v_mov_b32_e32 v108, v2
	v_mov_b32_e32 v109, v2
	v_mov_b32_e32 v110, v2
	v_mov_b32_e32 v111, v2
	v_mov_b32_e32 v112, v2
	v_mov_b32_e32 v113, v2
	v_mov_b32_e32 v122, v2
	v_mov_b32_e32 v123, v2
	v_mov_b32_e32 v124, v2
	v_mov_b32_e32 v125, v2
	v_mov_b32_e32 v126, v2
	v_mov_b32_e32 v127, v2
	v_mov_b32_e32 v128, v2
	v_mov_b32_e32 v129, v2

;   DI void operator()(const f32x4 (&acc)[2][2][4][2], const Unit& u, int wr, int wc, int fr, int fq) const {
;     ...
;           float ss = 0.f;
; #pragma unroll
;           for (int bj = 0; bj < 2; ++bj)
; #pragma unroll
;             for (int n = 0; n < 2; ++n)
; #pragma unroll
;               for (int e = 0; e < 4; ++e) ss += acc[ai][bj][m][n][e] * acc[ai][bj][m][n][e];
;           ss += __shfl_xor(ss, 16);
;           ss += __shfl_xor(ss, 32);
;           const float rinv = rsqrtf(ss * (1.f / 64.f) + EPSV);
;           float o1[8], o2[8];
; #pragma unroll
;           for (int n = 0; n < 2; ++n) {
;             f32x4 cs0 = (f32x4){1.f, 0.f, 1.f, 0.f}, cs1 = cs0;
;             if (ropeT) { cs0 = csr[m & 1][n][0]; cs1 = csr[m & 1][n][1]; }
; #pragma unroll
;             for (int e = 0; e < 4; ++e) {
;               float x1 = acc[ai][0][m][n][e] * (rinv * qs) * g4[0][n][e];
;               float x2 = acc[ai][1][m][n][e] * (rinv * qs) * g4[1][n][e];
;               float c = (e < 2) ? cs0[2 * e] : cs1[2 * (e - 2)], s = (e < 2) ? cs0[2 * e + 1] : cs1[2 * (e - 2) + 1];
;               o1[n * 4 + e] = x1 * c - x2 * s;
;               o2[n * 4 + e] = x2 * c + x1 * s;
;             }
;           }
;           u16* dst = base + (size_t)pos * 64 + 8 * fq;
;           *(uint4*)(dst) = make_uint4(pack_bf16(o1[0], o1[1]), pack_bf16(o1[2], o1[3]), pack_bf16(o1[4], o1[5]), pack_bf16(o1[6], o1[7]));
;           *(uint4*)(dst + 32) = make_uint4(pack_bf16(o2[0], o2[1]), pack_bf16(o2[2], o2[3]), pack_bf16(o2[4], o2[5]), pack_bf16(o2[6], o2[7]));
.LBB0_540:
	s_add_i32 s10, s50, s42
	s_and_b32 s11, s10, 0xfd0
	s_ashr_i32 s10, s10, 7
	s_andn2_b32 s10, s10, 31
	s_add_i32 s10, s10, s48
	v_or_b32_e32 v162, s11, v214
	s_mul_hi_i32 s11, s10, 0x88000
	s_mul_i32 s10, s10, 0x88000
	s_add_u32 s10, s88, s10
	s_addc_u32 s11, s89, s11
	s_and_b64 vcc, exec, s[8:9]
	s_mov_b64 s[22:23], -1
	v_readlane_b32 s52, v253, 59
	v_readlane_b32 s53, v253, 60
	s_cbranch_vccnz .LBB0_542
	v_mul_f32_e32 v163, v159, v159
	v_fmac_f32_e32 v163, v158, v158
	v_fmac_f32_e32 v163, v160, v160
	v_fmac_f32_e32 v163, v161, v161
	v_fmac_f32_e32 v163, v154, v154
	v_fmac_f32_e32 v163, v155, v155
	v_fmac_f32_e32 v163, v156, v156
	v_fmac_f32_e32 v163, v157, v157
	v_pk_mul_f32 v[166:167], v[150:151], v[150:151]
	v_pk_mul_f32 v[164:165], v[152:153], v[152:153]
	v_add_f32_e32 v163, v166, v163
	v_add_f32_e32 v163, v167, v163
	v_add_f32_e32 v163, v164, v163
	v_add_f32_e32 v163, v165, v163
	v_pk_mul_f32 v[166:167], v[146:147], v[146:147]
	v_pk_mul_f32 v[164:165], v[148:149], v[148:149]
	v_add_f32_e32 v163, v166, v163
	v_add_f32_e32 v163, v167, v163
	v_add_f32_e32 v163, v164, v163
	v_add_f32_e32 v163, v165, v163
	v_and_b32_e32 v165, 64, v211
	v_xor_b32_e32 v164, 16, v211
	v_add_u32_e32 v165, 64, v165
	v_cmp_lt_i32_e32 vcc, v164, v165
	s_mov_b32 s22, 0x800000
	v_mov_b32_e32 v174, v158
	v_cndmask_b32_e32 v164, v211, v164, vcc
	v_lshlrev_b32_e32 v164, 2, v164
	ds_bpermute_b32 v164, v164, v163
	v_mov_b32_e32 v175, v151
	v_mov_b32_e32 v176, v74
	v_mov_b32_e32 v177, v79
	v_mov_b32_e32 v218, v78
	s_waitcnt lgkmcnt(0)
	v_add_f32_e32 v163, v163, v164
	v_xor_b32_e32 v164, 32, v211
	v_cmp_lt_i32_e32 vcc, v164, v165
	v_mov_b32_e32 v219, v75
	v_cndmask_b32_e64 v167, 0, v97, s[6:7]
	v_cndmask_b32_e32 v164, v211, v164, vcc
	v_lshlrev_b32_e32 v164, 2, v164
	ds_bpermute_b32 v164, v164, v163
	v_cndmask_b32_e64 v166, 1.0, v94, s[6:7]
	v_cndmask_b32_e64 v169, 1.0, v96, s[6:7]
	v_cndmask_b32_e64 v168, 0, v95, s[6:7]
	v_mov_b32_e32 v221, v169
	s_waitcnt lgkmcnt(0)
	v_add_f32_e32 v163, v163, v164
	v_fmamk_f32 v163, v163, 0x3c800000, v210
	v_mul_f32_e32 v164, 0x4b800000, v163
	v_cmp_gt_f32_e32 vcc, s22, v163
	v_mov_b32_e32 v220, v166
	v_cndmask_b32_e64 v171, 0, v101, s[6:7]
	v_cndmask_b32_e32 v163, v163, v164, vcc
	v_rsq_f32_e32 v163, v163
	v_cndmask_b32_e64 v170, 1.0, v98, s[6:7]
	v_cndmask_b32_e64 v173, 1.0, v100, s[6:7]
	v_cndmask_b32_e64 v172, 0, v99, s[6:7]
	v_mul_f32_e32 v164, 0x45800000, v163
	v_cndmask_b32_e32 v163, v163, v164, vcc
	v_mul_f32_e32 v164, v217, v163
	v_pk_mul_f32 v[174:175], v[174:175], v[164:165] op_sel_hi:[1,0]
	v_mov_b32_e32 v224, v66
	v_pk_mul_f32 v[174:175], v[176:177], v[174:175]
	v_mov_b32_e32 v176, v150
	v_mov_b32_e32 v177, v159
	v_pk_mul_f32 v[176:177], v[176:177], v[164:165] op_sel_hi:[1,0]
	v_mov_b32_e32 v222, v174
	v_pk_mul_f32 v[176:177], v[218:219], v[176:177]
	v_mov_b32_e32 v225, v71
	v_pk_mul_f32 v[218:219], v[166:167], v[176:177]
	v_mov_b32_e32 v223, v177
	v_pk_fma_f32 v[218:219], v[168:169], v[174:175], v[218:219]
	v_mov_b32_e32 v169, v167
	v_mov_b32_e32 v177, v175
	v_pk_mul_f32 v[166:167], v[168:169], v[176:177]
	v_mov_b32_e32 v168, v160
	v_mov_b32_e32 v169, v153
	v_pk_mul_f32 v[168:169], v[168:169], v[164:165] op_sel_hi:[1,0]
	v_mov_b32_e32 v174, v76
	v_mov_b32_e32 v175, v81
	v_pk_mul_f32 v[168:169], v[174:175], v[168:169]
	v_mov_b32_e32 v174, v152
	v_mov_b32_e32 v175, v161
	v_pk_mul_f32 v[174:175], v[174:175], v[164:165] op_sel_hi:[1,0]
	v_mov_b32_e32 v176, v80
	v_mov_b32_e32 v177, v77
	v_pk_mul_f32 v[174:175], v[176:177], v[174:175]
	v_pk_fma_f32 v[166:167], v[220:221], v[222:223], v[166:167] neg_lo:[0,0,1] neg_hi:[0,0,1]
	v_pk_mul_f32 v[176:177], v[170:171], v[174:175]
	v_mov_b32_e32 v221, v173
	v_pk_fma_f32 v[176:177], v[172:173], v[168:169], v[176:177]
	v_mov_b32_e32 v223, v175
	v_mov_b32_e32 v173, v171
	v_mov_b32_e32 v175, v169
	v_mov_b32_e32 v220, v170
	v_mov_b32_e32 v222, v168
	v_pk_mul_f32 v[168:169], v[172:173], v[174:175]
	v_mov_b32_e32 v226, v70
	v_pk_fma_f32 v[168:169], v[220:221], v[222:223], v[168:169] neg_lo:[0,0,1] neg_hi:[0,0,1]
	v_mov_b32_e32 v222, v154
	v_mov_b32_e32 v223, v147
	v_pk_mul_f32 v[222:223], v[222:223], v[164:165] op_sel_hi:[1,0]
	v_mov_b32_e32 v227, v67
	v_pk_mul_f32 v[222:223], v[224:225], v[222:223]
	v_mov_b32_e32 v224, v146
	v_mov_b32_e32 v225, v155
	v_pk_mul_f32 v[224:225], v[224:225], v[164:165] op_sel_hi:[1,0]
	v_cndmask_b32_e64 v171, 0, v89, s[6:7]
	v_cndmask_b32_e64 v170, 1.0, v86, s[6:7]
	v_pk_mul_f32 v[224:225], v[226:227], v[224:225]
	v_cndmask_b32_e64 v173, 1.0, v88, s[6:7]
	v_cndmask_b32_e64 v172, 0, v87, s[6:7]
	v_pk_mul_f32 v[226:227], v[170:171], v[224:225]
	v_mov_b32_e32 v229, v173
	v_pk_fma_f32 v[226:227], v[172:173], v[222:223], v[226:227]
	v_mov_b32_e32 v231, v225
	v_mov_b32_e32 v173, v171
	v_mov_b32_e32 v225, v223
	v_mov_b32_e32 v228, v170
	v_pk_mul_f32 v[170:171], v[172:173], v[224:225]
	v_mov_b32_e32 v172, v156
	v_mov_b32_e32 v173, v149
	v_mov_b32_e32 v230, v222
	v_pk_mul_f32 v[172:173], v[172:173], v[164:165] op_sel_hi:[1,0]
	v_mov_b32_e32 v222, v68
	v_mov_b32_e32 v223, v73
	v_pk_mul_f32 v[172:173], v[222:223], v[172:173]
	v_mov_b32_e32 v222, v148
	v_mov_b32_e32 v223, v157
	v_pk_mul_f32 v[164:165], v[222:223], v[164:165] op_sel_hi:[1,0]
	v_mov_b32_e32 v222, v72
	v_mov_b32_e32 v223, v69
	v_cndmask_b32_e64 v175, 0, v85, s[6:7]
	v_cndmask_b32_e64 v174, 1.0, v82, s[6:7]
	v_pk_mul_f32 v[164:165], v[222:223], v[164:165]
	v_cndmask_b32_e64 v221, 1.0, v84, s[6:7]
	v_cndmask_b32_e64 v220, 0, v83, s[6:7]
	v_pk_mul_f32 v[222:223], v[174:175], v[164:165]
	v_pk_fma_f32 v[170:171], v[228:229], v[230:231], v[170:171] neg_lo:[0,0,1] neg_hi:[0,0,1]
	v_pk_fma_f32 v[222:223], v[220:221], v[172:173], v[222:223]
	v_mov_b32_e32 v225, v221
	v_mov_b32_e32 v229, v165
	v_mov_b32_e32 v221, v175
	v_mov_b32_e32 v165, v173
	v_mov_b32_e32 v224, v174
	v_mov_b32_e32 v228, v172
	v_pk_mul_f32 v[164:165], v[220:221], v[164:165]
	v_mov_b32_e32 v207, v1
	v_pk_fma_f32 v[172:173], v[224:225], v[228:229], v[164:165] neg_lo:[0,0,1] neg_hi:[0,0,1]
	v_lshlrev_b32_e32 v164, 7, v162
	v_mov_b32_e32 v165, v1
	v_lshl_add_u64 v[164:165], s[10:11], 0, v[164:165]
	v_lshl_add_u64 v[174:175], v[164:165], 0, v[206:207]
	v_cvt_pk_bf16_f32 v164, v166, v167
	v_cvt_pk_bf16_f32 v165, v168, v169
	v_cvt_pk_bf16_f32 v166, v170, v171
	v_cvt_pk_bf16_f32 v167, v172, v173
	global_store_dwordx4 v[174:175], v[164:167], off
	s_mov_b64 s[22:23], 0
	s_nop 0
	v_cvt_pk_bf16_f32 v164, v218, v219
	v_cvt_pk_bf16_f32 v165, v176, v177
	v_cvt_pk_bf16_f32 v166, v226, v227
	v_cvt_pk_bf16_f32 v167, v222, v223
	global_store_dwordx4 v[174:175], v[164:167], off offset:64

;   DI void operator()(const f32x4 (&acc)[2][2][4][2], const Unit& u, int wr, int wc, int fr, int fq) const {
;     ...
;       if (ropeT && !isV) {
; #pragma unroll
;         for (int m2 = 0; m2 < 2; ++m2) {
;           const int tt = u.pm * BM + ai * HALF + wr * 64 + (2 * mp + m2) * 16 + fr;
;           const float* rp = rope + (size_t)(tt & 4095) * 64 + 2 * (8 * fq);
; #pragma unroll
;           for (int n = 0; n < 2; ++n) { csr[m2][n][0] = *(const f32x4*)(rp + 8 * n); csr[m2][n][1] = *(const f32x4*)(rp + 8 * n + 4); }
;         }
;       }
.LBB0_544:
	s_xor_b64 s[2:3], s[2:3], -1
	v_cndmask_b32_e64 v146, 0, 1, s[2:3]
	v_cmp_ne_u32_e64 s[10:11], 1, v146
	s_andn2_b64 vcc, exec, s[2:3]
	s_cbranch_vccnz .LBB0_546
	v_lshl_add_u64 v[82:83], v[196:197], 0, v[0:1]
	s_mov_b64 s[2:3], 0x2000
	v_add_co_u32_e32 v86, vcc, 0x2000, v82
	v_lshl_add_u64 v[84:85], v[82:83], 0, s[2:3]
	s_nop 0
	v_addc_co_u32_e32 v87, vcc, 0, v83, vcc
	s_mov_b64 s[2:3], 0x3000
	v_lshl_add_u64 v[98:99], v[82:83], 0, s[2:3]
	v_add_co_u32_e32 v82, vcc, 0x3000, v82
	global_load_dwordx4 v[126:129], v[86:87], off
	global_load_dwordx4 v[114:117], v[84:85], off offset:48
	global_load_dwordx4 v[118:121], v[84:85], off offset:32
	global_load_dwordx4 v[122:125], v[84:85], off offset:16
	v_addc_co_u32_e32 v83, vcc, 0, v83, vcc
	global_load_dwordx4 v[94:97], v[82:83], off
	s_nop 0
	global_load_dwordx4 v[82:85], v[98:99], off offset:48
	global_load_dwordx4 v[86:89], v[98:99], off offset:32
	s_nop 0
	global_load_dwordx4 v[98:101], v[98:99], off offset:16

;   DI void operator()(const f32x4 (&acc)[2][2][4][2], const Unit& u, int wr, int wc, int fr, int fq) const {
;     ...
;           float ss = 0.f;
; #pragma unroll
;           for (int bj = 0; bj < 2; ++bj)
; #pragma unroll
;             for (int n = 0; n < 2; ++n)
; #pragma unroll
;               for (int e = 0; e < 4; ++e) ss += acc[ai][bj][m][n][e] * acc[ai][bj][m][n][e];
;           ss += __shfl_xor(ss, 16);
;           ss += __shfl_xor(ss, 32);
;           const float rinv = rsqrtf(ss * (1.f / 64.f) + EPSV);
;           float o1[8], o2[8];
; #pragma unroll
;           for (int n = 0; n < 2; ++n) {
;             f32x4 cs0 = (f32x4){1.f, 0.f, 1.f, 0.f}, cs1 = cs0;
;             if (ropeT) { cs0 = csr[m & 1][n][0]; cs1 = csr[m & 1][n][1]; }
; #pragma unroll
;             for (int e = 0; e < 4; ++e) {
;               float x1 = acc[ai][0][m][n][e] * (rinv * qs) * g4[0][n][e];
;               float x2 = acc[ai][1][m][n][e] * (rinv * qs) * g4[1][n][e];
;               float c = (e < 2) ? cs0[2 * e] : cs1[2 * (e - 2)], s = (e < 2) ? cs0[2 * e + 1] : cs1[2 * (e - 2) + 1];
;               o1[n * 4 + e] = x1 * c - x2 * s;
;               o2[n * 4 + e] = x2 * c + x1 * s;
;             }
;           }
;           u16* dst = base + (size_t)pos * 64 + 8 * fq;
;           *(uint4*)(dst) = make_uint4(pack_bf16(o1[0], o1[1]), pack_bf16(o1[2], o1[3]), pack_bf16(o1[4], o1[5]), pack_bf16(o1[6], o1[7]));
;           *(uint4*)(dst + 32) = make_uint4(pack_bf16(o2[0], o2[1]), pack_bf16(o2[2], o2[3]), pack_bf16(o2[4], o2[5]), pack_bf16(o2[6], o2[7]));
.LBB0_550:
	s_add_i32 s50, s50, s44
	s_and_b32 s2, s50, 0xff0
	v_or_b32_e32 v130, s2, v214
	s_ashr_i32 s2, s50, 7
	s_andn2_b32 s2, s2, 31
	s_add_i32 s2, s2, s48
	s_mul_hi_i32 s3, s2, 0x88000
	s_mul_i32 s2, s2, 0x88000
	s_add_u32 s2, s88, s2
	s_addc_u32 s3, s89, s3
	s_and_b64 vcc, exec, s[8:9]
	s_mov_b64 s[22:23], -1
	s_cbranch_vccnz .LBB0_552
	v_mul_f32_e32 v0, v111, v111
	v_fmac_f32_e32 v0, v110, v110
	v_fmac_f32_e32 v0, v112, v112
	v_fmac_f32_e32 v0, v113, v113
	v_fmac_f32_e32 v0, v106, v106
	v_fmac_f32_e32 v0, v107, v107
	v_fmac_f32_e32 v0, v108, v108
	v_fmac_f32_e32 v0, v109, v109
	v_pk_mul_f32 v[134:135], v[102:103], v[102:103]
	v_pk_mul_f32 v[132:133], v[104:105], v[104:105]
	v_add_f32_e32 v0, v134, v0
	v_add_f32_e32 v0, v135, v0
	v_add_f32_e32 v0, v132, v0
	v_add_f32_e32 v0, v133, v0
	v_pk_mul_f32 v[134:135], v[90:91], v[90:91]
	v_pk_mul_f32 v[132:133], v[92:93], v[92:93]
	v_add_f32_e32 v0, v134, v0
	v_add_f32_e32 v0, v135, v0
	v_add_f32_e32 v0, v132, v0
	v_and_b32_e32 v132, 64, v211
	v_xor_b32_e32 v131, 16, v211
	v_add_u32_e32 v132, 64, v132
	v_cmp_lt_i32_e32 vcc, v131, v132
	v_add_f32_e32 v0, v133, v0
	s_mov_b32 s22, 0x800000
	v_cndmask_b32_e32 v131, v211, v131, vcc
	v_lshlrev_b32_e32 v131, 2, v131
	ds_bpermute_b32 v131, v131, v0
	v_mov_b32_e32 v140, v110
	v_mov_b32_e32 v141, v103
	v_mov_b32_e32 v142, v74
	v_mov_b32_e32 v143, v79
	s_waitcnt lgkmcnt(0)
	v_add_f32_e32 v0, v0, v131
	v_xor_b32_e32 v131, 32, v211
	v_cmp_lt_i32_e32 vcc, v131, v132
	v_mov_b32_e32 v144, v78
	v_mov_b32_e32 v145, v75
	v_cndmask_b32_e32 v131, v211, v131, vcc
	v_lshlrev_b32_e32 v131, 2, v131
	ds_bpermute_b32 v131, v131, v0
	v_cndmask_b32_e64 v133, 0, v97, s[6:7]
	v_cndmask_b32_e64 v132, 1.0, v94, s[6:7]
	v_cndmask_b32_e64 v135, 1.0, v96, s[6:7]
	v_cndmask_b32_e64 v134, 0, v95, s[6:7]
	s_waitcnt lgkmcnt(0)
	v_add_f32_e32 v0, v0, v131
	v_fmamk_f32 v0, v0, 0x3c800000, v210
	v_mul_f32_e32 v131, 0x4b800000, v0
	v_cmp_gt_f32_e32 vcc, s22, v0
	v_mov_b32_e32 v147, v135
	v_mov_b32_e32 v146, v132
	v_cndmask_b32_e32 v0, v0, v131, vcc
	v_rsq_f32_e32 v0, v0
	v_cndmask_b32_e64 v137, 0, v101, s[6:7]
	v_cndmask_b32_e64 v136, 1.0, v98, s[6:7]
	v_cndmask_b32_e64 v139, 1.0, v100, s[6:7]
	v_mul_f32_e32 v131, 0x45800000, v0
	v_cndmask_b32_e32 v0, v0, v131, vcc
	v_mul_f32_e32 v0, v217, v0
	v_pk_mul_f32 v[140:141], v[140:141], v[0:1] op_sel_hi:[1,0]
	v_cndmask_b32_e64 v138, 0, v99, s[6:7]
	v_pk_mul_f32 v[140:141], v[142:143], v[140:141]
	v_mov_b32_e32 v142, v102
	v_mov_b32_e32 v143, v111
	v_pk_mul_f32 v[142:143], v[142:143], v[0:1] op_sel_hi:[1,0]
	v_mov_b32_e32 v148, v140
	v_pk_mul_f32 v[142:143], v[144:145], v[142:143]
	v_mov_b32_e32 v150, v66
	v_pk_mul_f32 v[144:145], v[132:133], v[142:143]
	v_mov_b32_e32 v149, v143
	v_pk_fma_f32 v[144:145], v[134:135], v[140:141], v[144:145]
	v_mov_b32_e32 v135, v133
	v_mov_b32_e32 v143, v141
	v_pk_mul_f32 v[132:133], v[134:135], v[142:143]
	v_mov_b32_e32 v134, v112
	v_mov_b32_e32 v135, v105
	v_pk_mul_f32 v[134:135], v[134:135], v[0:1] op_sel_hi:[1,0]
	v_mov_b32_e32 v140, v76
	v_mov_b32_e32 v141, v81
	v_pk_mul_f32 v[134:135], v[140:141], v[134:135]
	v_mov_b32_e32 v140, v104
	v_mov_b32_e32 v141, v113
	v_pk_mul_f32 v[140:141], v[140:141], v[0:1] op_sel_hi:[1,0]
	v_mov_b32_e32 v142, v80
	v_mov_b32_e32 v143, v77
	v_pk_mul_f32 v[140:141], v[142:143], v[140:141]
	v_pk_fma_f32 v[132:133], v[146:147], v[148:149], v[132:133] neg_lo:[0,0,1] neg_hi:[0,0,1]
	v_pk_mul_f32 v[142:143], v[136:137], v[140:141]
	v_mov_b32_e32 v147, v139
	v_pk_fma_f32 v[142:143], v[138:139], v[134:135], v[142:143]
	v_mov_b32_e32 v149, v141
	v_mov_b32_e32 v139, v137
	v_mov_b32_e32 v141, v135
	v_mov_b32_e32 v146, v136
	v_mov_b32_e32 v148, v134
	v_pk_mul_f32 v[134:135], v[138:139], v[140:141]
	v_mov_b32_e32 v151, v71
	v_pk_fma_f32 v[134:135], v[146:147], v[148:149], v[134:135] neg_lo:[0,0,1] neg_hi:[0,0,1]
	v_mov_b32_e32 v148, v106
	v_mov_b32_e32 v149, v91
	v_pk_mul_f32 v[148:149], v[148:149], v[0:1] op_sel_hi:[1,0]
	v_mov_b32_e32 v152, v70
	v_pk_mul_f32 v[148:149], v[150:151], v[148:149]
	v_mov_b32_e32 v150, v90
	v_mov_b32_e32 v151, v107
	v_pk_mul_f32 v[150:151], v[150:151], v[0:1] op_sel_hi:[1,0]
	v_mov_b32_e32 v153, v67
	v_cndmask_b32_e64 v137, 0, v89, s[6:7]
	v_cndmask_b32_e64 v136, 1.0, v86, s[6:7]
	v_pk_mul_f32 v[150:151], v[152:153], v[150:151]
	v_cndmask_b32_e64 v139, 1.0, v88, s[6:7]
	v_cndmask_b32_e64 v138, 0, v87, s[6:7]
	v_pk_mul_f32 v[152:153], v[136:137], v[150:151]
	v_mov_b32_e32 v155, v139
	v_pk_fma_f32 v[152:153], v[138:139], v[148:149], v[152:153]
	v_mov_b32_e32 v157, v151
	v_mov_b32_e32 v139, v137
	v_mov_b32_e32 v151, v149
	v_mov_b32_e32 v154, v136
	v_pk_mul_f32 v[136:137], v[138:139], v[150:151]
	v_mov_b32_e32 v138, v108
	v_mov_b32_e32 v139, v93
	v_mov_b32_e32 v156, v148
	v_pk_mul_f32 v[138:139], v[138:139], v[0:1] op_sel_hi:[1,0]
	v_mov_b32_e32 v148, v68
	v_mov_b32_e32 v149, v73
	v_pk_mul_f32 v[138:139], v[148:149], v[138:139]
	v_mov_b32_e32 v148, v92
	v_mov_b32_e32 v149, v109
	v_pk_mul_f32 v[148:149], v[148:149], v[0:1] op_sel_hi:[1,0]
	v_mov_b32_e32 v150, v72
	v_mov_b32_e32 v151, v69
	v_cndmask_b32_e64 v141, 0, v85, s[6:7]
	v_cndmask_b32_e64 v140, 1.0, v82, s[6:7]
	v_pk_mul_f32 v[148:149], v[150:151], v[148:149]
	v_cndmask_b32_e64 v147, 1.0, v84, s[6:7]
	v_cndmask_b32_e64 v146, 0, v83, s[6:7]
	v_pk_mul_f32 v[150:151], v[140:141], v[148:149]
	v_pk_fma_f32 v[136:137], v[154:155], v[156:157], v[136:137] neg_lo:[0,0,1] neg_hi:[0,0,1]
	v_pk_fma_f32 v[150:151], v[146:147], v[138:139], v[150:151]
	v_mov_b32_e32 v155, v147
	v_mov_b32_e32 v157, v149
	v_mov_b32_e32 v147, v141
	v_mov_b32_e32 v149, v139
	v_mov_b32_e32 v154, v140
	v_mov_b32_e32 v156, v138
	v_pk_mul_f32 v[138:139], v[146:147], v[148:149]
	v_lshlrev_b32_e32 v0, 7, v130
	v_pk_fma_f32 v[138:139], v[154:155], v[156:157], v[138:139] neg_lo:[0,0,1] neg_hi:[0,0,1]
	v_lshl_add_u64 v[140:141], s[2:3], 0, v[0:1]
	v_mov_b32_e32 v207, v1
	v_lshl_add_u64 v[140:141], v[140:141], 0, v[206:207]
	v_cvt_pk_bf16_f32 v132, v132, v133
	v_cvt_pk_bf16_f32 v133, v134, v135
	v_cvt_pk_bf16_f32 v134, v136, v137
	v_cvt_pk_bf16_f32 v135, v138, v139
	global_store_dwordx4 v[140:141], v[132:135], off
	s_mov_b64 s[22:23], 0
	s_nop 0
	v_cvt_pk_bf16_f32 v132, v144, v145
	v_cvt_pk_bf16_f32 v133, v142, v143
	v_cvt_pk_bf16_f32 v134, v152, v153
	v_cvt_pk_bf16_f32 v135, v150, v151
	global_store_dwordx4 v[140:141], v[132:135], off offset:64

;   DI void operator()(const f32x4 (&acc)[2][2][4][2], const Unit& u, int wr, int wc, int fr, int fq) const {
;     ...
;       if (ropeT && !isV) {
; #pragma unroll
;         for (int m2 = 0; m2 < 2; ++m2) {
;           const int tt = u.pm * BM + ai * HALF + wr * 64 + (2 * mp + m2) * 16 + fr;
;           const float* rp = rope + (size_t)(tt & 4095) * 64 + 2 * (8 * fq);
; #pragma unroll
;           for (int n = 0; n < 2; ++n) { csr[m2][n][0] = *(const f32x4*)(rp + 8 * n); csr[m2][n][1] = *(const f32x4*)(rp + 8 * n + 4); }
;         }
;       }
.LBB0_554:
	s_add_i32 s2, s49, 0x80
	s_and_b32 s3, s2, 0xfc0
	v_or_b32_e32 v90, s3, v214
	s_and_b64 vcc, exec, s[10:11]
	v_lshlrev_b32_e32 v0, 8, v90
	s_cbranch_vccnz .LBB0_556
	v_lshl_add_u64 v[82:83], v[196:197], 0, v[0:1]
	s_mov_b64 s[22:23], 0x1000
	global_load_dwordx4 v[114:117], v[82:83], off offset:48
	global_load_dwordx4 v[118:121], v[82:83], off offset:32
	global_load_dwordx4 v[122:125], v[82:83], off offset:16
	global_load_dwordx4 v[126:129], v[82:83], off
	v_lshl_add_u64 v[92:93], v[82:83], 0, s[22:23]
	v_add_co_u32_e32 v82, vcc, 0x1000, v82
	s_nop 1
	v_addc_co_u32_e32 v83, vcc, 0, v83, vcc
	global_load_dwordx4 v[94:97], v[82:83], off
	s_nop 0
	global_load_dwordx4 v[82:85], v[92:93], off offset:48
	global_load_dwordx4 v[86:89], v[92:93], off offset:32
	global_load_dwordx4 v[98:101], v[92:93], off offset:16

;   DI void operator()(const f32x4 (&acc)[2][2][4][2], const Unit& u, int wr, int wc, int fr, int fq) const {
;     ...
;           float ss = 0.f;
; #pragma unroll
;           for (int bj = 0; bj < 2; ++bj)
; #pragma unroll
;             for (int n = 0; n < 2; ++n)
; #pragma unroll
;               for (int e = 0; e < 4; ++e) ss += acc[ai][bj][m][n][e] * acc[ai][bj][m][n][e];
;           ss += __shfl_xor(ss, 16);
;           ss += __shfl_xor(ss, 32);
;           const float rinv = rsqrtf(ss * (1.f / 64.f) + EPSV);
;           float o1[8], o2[8];
; #pragma unroll
;           for (int n = 0; n < 2; ++n) {
;             f32x4 cs0 = (f32x4){1.f, 0.f, 1.f, 0.f}, cs1 = cs0;
;             if (ropeT) { cs0 = csr[m & 1][n][0]; cs1 = csr[m & 1][n][1]; }
; #pragma unroll
;             for (int e = 0; e < 4; ++e) {
;               float x1 = acc[ai][0][m][n][e] * (rinv * qs) * g4[0][n][e];
;               float x2 = acc[ai][1][m][n][e] * (rinv * qs) * g4[1][n][e];
;               float c = (e < 2) ? cs0[2 * e] : cs1[2 * (e - 2)], s = (e < 2) ? cs0[2 * e + 1] : cs1[2 * (e - 2) + 1];
;               o1[n * 4 + e] = x1 * c - x2 * s;
;               o2[n * 4 + e] = x2 * c + x1 * s;
;             }
;           }
;           u16* dst = base + (size_t)pos * 64 + 8 * fq;
;           *(uint4*)(dst) = make_uint4(pack_bf16(o1[0], o1[1]), pack_bf16(o1[2], o1[3]), pack_bf16(o1[4], o1[5]), pack_bf16(o1[6], o1[7]));
;           *(uint4*)(dst + 32) = make_uint4(pack_bf16(o2[0], o2[1]), pack_bf16(o2[2], o2[3]), pack_bf16(o2[4], o2[5]), pack_bf16(o2[6], o2[7]));
.LBB0_560:
	s_add_i32 s2, s49, 0x90
	s_and_b32 s3, s2, 0xfd0
	s_ashr_i32 s2, s2, 7
	s_andn2_b32 s2, s2, 31
	s_add_i32 s2, s2, s48
	v_or_b32_e32 v50, s3, v214
	s_mul_hi_i32 s3, s2, 0x88000
	s_mul_i32 s2, s2, 0x88000
	s_add_u32 s2, s88, s2
	s_addc_u32 s3, s89, s3
	s_and_b64 vcc, exec, s[8:9]
	s_mov_b64 s[22:23], -1
	s_cbranch_vccnz .LBB0_572
	v_mul_f32_e32 v51, v47, v47
	v_fmac_f32_e32 v51, v46, v46
	v_fmac_f32_e32 v51, v48, v48
	v_fmac_f32_e32 v51, v49, v49
	v_fmac_f32_e32 v51, v42, v42
	v_fmac_f32_e32 v51, v43, v43
	v_fmac_f32_e32 v51, v44, v44
	v_fmac_f32_e32 v51, v45, v45
	v_pk_mul_f32 v[54:55], v[38:39], v[38:39]
	v_pk_mul_f32 v[52:53], v[40:41], v[40:41]
	v_add_f32_e32 v51, v54, v51
	v_add_f32_e32 v51, v55, v51
	v_add_f32_e32 v51, v52, v51
	v_add_f32_e32 v51, v53, v51
	v_pk_mul_f32 v[54:55], v[34:35], v[34:35]
	v_pk_mul_f32 v[52:53], v[36:37], v[36:37]
	v_add_f32_e32 v51, v54, v51
	v_add_f32_e32 v51, v55, v51
	v_add_f32_e32 v51, v52, v51
	v_add_f32_e32 v51, v53, v51
	v_and_b32_e32 v53, 64, v211
	v_xor_b32_e32 v52, 16, v211
	v_add_u32_e32 v53, 64, v53
	v_cmp_lt_i32_e32 vcc, v52, v53
	s_mov_b32 s22, 0x800000
	v_mov_b32_e32 v62, v46
	v_cndmask_b32_e32 v52, v211, v52, vcc
	v_lshlrev_b32_e32 v52, 2, v52
	ds_bpermute_b32 v52, v52, v51
	v_mov_b32_e32 v63, v39
	v_mov_b32_e32 v64, v74
	v_mov_b32_e32 v65, v79
	v_mov_b32_e32 v90, v78
	s_waitcnt lgkmcnt(0)
	v_add_f32_e32 v51, v51, v52
	v_xor_b32_e32 v52, 32, v211
	v_cmp_lt_i32_e32 vcc, v52, v53
	v_mov_b32_e32 v91, v75
	v_cndmask_b32_e64 v55, 0, v97, s[6:7]
	v_cndmask_b32_e32 v52, v211, v52, vcc
	v_lshlrev_b32_e32 v52, 2, v52
	ds_bpermute_b32 v52, v52, v51
	v_cndmask_b32_e64 v54, 1.0, v94, s[6:7]
	v_cndmask_b32_e64 v57, 1.0, v96, s[6:7]
	v_cndmask_b32_e64 v56, 0, v95, s[6:7]
	v_mov_b32_e32 v93, v57
	s_waitcnt lgkmcnt(0)
	v_add_f32_e32 v51, v51, v52
	v_fmamk_f32 v51, v51, 0x3c800000, v210
	v_mul_f32_e32 v52, 0x4b800000, v51
	v_cmp_gt_f32_e32 vcc, s22, v51
	v_mov_b32_e32 v92, v54
	v_cndmask_b32_e64 v59, 0, v101, s[6:7]
	v_cndmask_b32_e32 v51, v51, v52, vcc
	v_rsq_f32_e32 v51, v51
	v_cndmask_b32_e64 v58, 1.0, v98, s[6:7]
	v_cndmask_b32_e64 v61, 1.0, v100, s[6:7]
	v_cndmask_b32_e64 v60, 0, v99, s[6:7]
	v_mul_f32_e32 v52, 0x45800000, v51
	v_cndmask_b32_e32 v51, v51, v52, vcc
	v_mul_f32_e32 v52, v217, v51
	v_pk_mul_f32 v[62:63], v[62:63], v[52:53] op_sel_hi:[1,0]
	v_mov_b32_e32 v104, v66
	v_pk_mul_f32 v[62:63], v[64:65], v[62:63]
	v_mov_b32_e32 v64, v38
	v_mov_b32_e32 v65, v47
	v_pk_mul_f32 v[64:65], v[64:65], v[52:53] op_sel_hi:[1,0]
	v_mov_b32_e32 v102, v62
	v_pk_mul_f32 v[64:65], v[90:91], v[64:65]
	v_mov_b32_e32 v105, v71
	v_pk_mul_f32 v[90:91], v[54:55], v[64:65]
	v_mov_b32_e32 v103, v65
	v_pk_fma_f32 v[90:91], v[56:57], v[62:63], v[90:91]
	v_mov_b32_e32 v57, v55
	v_mov_b32_e32 v65, v63
	v_pk_mul_f32 v[54:55], v[56:57], v[64:65]
	v_mov_b32_e32 v56, v48
	v_mov_b32_e32 v57, v41
	v_pk_mul_f32 v[56:57], v[56:57], v[52:53] op_sel_hi:[1,0]
	v_mov_b32_e32 v62, v76
	v_mov_b32_e32 v63, v81
	v_pk_mul_f32 v[56:57], v[62:63], v[56:57]
	v_mov_b32_e32 v62, v40
	v_mov_b32_e32 v63, v49
	v_pk_mul_f32 v[62:63], v[62:63], v[52:53] op_sel_hi:[1,0]
	v_mov_b32_e32 v64, v80
	v_mov_b32_e32 v65, v77
	v_pk_mul_f32 v[62:63], v[64:65], v[62:63]
	v_pk_fma_f32 v[54:55], v[92:93], v[102:103], v[54:55] neg_lo:[0,0,1] neg_hi:[0,0,1]
	v_pk_mul_f32 v[64:65], v[58:59], v[62:63]
	v_mov_b32_e32 v93, v61
	v_pk_fma_f32 v[64:65], v[60:61], v[56:57], v[64:65]
	v_mov_b32_e32 v103, v63
	v_mov_b32_e32 v61, v59
	v_mov_b32_e32 v63, v57
	v_mov_b32_e32 v92, v58
	v_mov_b32_e32 v102, v56
	v_pk_mul_f32 v[56:57], v[60:61], v[62:63]
	v_mov_b32_e32 v106, v70
	v_pk_fma_f32 v[56:57], v[92:93], v[102:103], v[56:57] neg_lo:[0,0,1] neg_hi:[0,0,1]
	v_mov_b32_e32 v102, v42
	v_mov_b32_e32 v103, v35
	v_pk_mul_f32 v[102:103], v[102:103], v[52:53] op_sel_hi:[1,0]
	v_mov_b32_e32 v107, v67
	v_pk_mul_f32 v[102:103], v[104:105], v[102:103]
	v_mov_b32_e32 v104, v34
	v_mov_b32_e32 v105, v43
	v_pk_mul_f32 v[104:105], v[104:105], v[52:53] op_sel_hi:[1,0]
	v_cndmask_b32_e64 v59, 0, v89, s[6:7]
	v_cndmask_b32_e64 v58, 1.0, v86, s[6:7]
	v_pk_mul_f32 v[104:105], v[106:107], v[104:105]
	v_cndmask_b32_e64 v61, 1.0, v88, s[6:7]
	v_cndmask_b32_e64 v60, 0, v87, s[6:7]
	v_pk_mul_f32 v[106:107], v[58:59], v[104:105]
	v_mov_b32_e32 v109, v61
	v_pk_fma_f32 v[106:107], v[60:61], v[102:103], v[106:107]
	v_mov_b32_e32 v111, v105
	v_mov_b32_e32 v61, v59
	v_mov_b32_e32 v105, v103
	v_mov_b32_e32 v108, v58
	v_pk_mul_f32 v[58:59], v[60:61], v[104:105]
	v_mov_b32_e32 v60, v44
	v_mov_b32_e32 v61, v37
	v_mov_b32_e32 v110, v102
	v_pk_mul_f32 v[60:61], v[60:61], v[52:53] op_sel_hi:[1,0]
	v_mov_b32_e32 v102, v68
	v_mov_b32_e32 v103, v73
	v_pk_mul_f32 v[60:61], v[102:103], v[60:61]
	v_mov_b32_e32 v102, v36
	v_mov_b32_e32 v103, v45
	v_pk_mul_f32 v[52:53], v[102:103], v[52:53] op_sel_hi:[1,0]
	v_mov_b32_e32 v102, v72
	v_mov_b32_e32 v103, v69
	v_cndmask_b32_e64 v63, 0, v85, s[6:7]
	v_cndmask_b32_e64 v62, 1.0, v82, s[6:7]
	v_pk_mul_f32 v[52:53], v[102:103], v[52:53]
	v_cndmask_b32_e64 v93, 1.0, v84, s[6:7]
	v_cndmask_b32_e64 v92, 0, v83, s[6:7]
	v_pk_mul_f32 v[102:103], v[62:63], v[52:53]
	v_pk_fma_f32 v[58:59], v[108:109], v[110:111], v[58:59] neg_lo:[0,0,1] neg_hi:[0,0,1]
	v_pk_fma_f32 v[102:103], v[92:93], v[60:61], v[102:103]
	v_mov_b32_e32 v105, v93
	v_mov_b32_e32 v109, v53
	v_mov_b32_e32 v93, v63
	v_mov_b32_e32 v53, v61
	v_mov_b32_e32 v104, v62
	v_mov_b32_e32 v108, v60
	v_pk_mul_f32 v[52:53], v[92:93], v[52:53]
	v_mov_b32_e32 v207, v1
	v_pk_fma_f32 v[60:61], v[104:105], v[108:109], v[52:53] neg_lo:[0,0,1] neg_hi:[0,0,1]
	v_lshlrev_b32_e32 v52, 7, v50
	v_mov_b32_e32 v53, v1
	v_lshl_add_u64 v[52:53], s[2:3], 0, v[52:53]
	v_lshl_add_u64 v[62:63], v[52:53], 0, v[206:207]
	v_cvt_pk_bf16_f32 v52, v54, v55
	v_cvt_pk_bf16_f32 v53, v56, v57
	v_cvt_pk_bf16_f32 v54, v58, v59
	v_cvt_pk_bf16_f32 v55, v60, v61
	global_store_dwordx4 v[62:63], v[52:55], off
	s_nop 1
	v_cvt_pk_bf16_f32 v52, v90, v91
	v_cvt_pk_bf16_f32 v53, v64, v65
	v_cvt_pk_bf16_f32 v54, v106, v107
	v_cvt_pk_bf16_f32 v55, v102, v103
	global_store_dwordx4 v[62:63], v[52:55], off offset:64
	s_cbranch_execz .LBB0_573

;   DI void operator()(const f32x4 (&acc)[2][2][4][2], const Unit& u, int wr, int wc, int fr, int fq) const {
;     ...
;           float ss = 0.f;
; #pragma unroll
;           for (int bj = 0; bj < 2; ++bj)
; #pragma unroll
;             for (int n = 0; n < 2; ++n)
; #pragma unroll
;               for (int e = 0; e < 4; ++e) ss += acc[ai][bj][m][n][e] * acc[ai][bj][m][n][e];
;           ss += __shfl_xor(ss, 16);
;           ss += __shfl_xor(ss, 32);
;           const float rinv = rsqrtf(ss * (1.f / 64.f) + EPSV);
;           float o1[8], o2[8];
; #pragma unroll
;           for (int n = 0; n < 2; ++n) {
;             f32x4 cs0 = (f32x4){1.f, 0.f, 1.f, 0.f}, cs1 = cs0;
;             if (ropeT) { cs0 = csr[m & 1][n][0]; cs1 = csr[m & 1][n][1]; }
; #pragma unroll
;             for (int e = 0; e < 4; ++e) {
;               float x1 = acc[ai][0][m][n][e] * (rinv * qs) * g4[0][n][e];
;               float x2 = acc[ai][1][m][n][e] * (rinv * qs) * g4[1][n][e];
;               float c = (e < 2) ? cs0[2 * e] : cs1[2 * (e - 2)], s = (e < 2) ? cs0[2 * e + 1] : cs1[2 * (e - 2) + 1];
;               o1[n * 4 + e] = x1 * c - x2 * s;
;               o2[n * 4 + e] = x2 * c + x1 * s;
;             }
;           }
;           u16* dst = base + (size_t)pos * 64 + 8 * fq;
;           *(uint4*)(dst) = make_uint4(pack_bf16(o1[0], o1[1]), pack_bf16(o1[2], o1[3]), pack_bf16(o1[4], o1[5]), pack_bf16(o1[6], o1[7]));
;           *(uint4*)(dst + 32) = make_uint4(pack_bf16(o2[0], o2[1]), pack_bf16(o2[2], o2[3]), pack_bf16(o2[4], o2[5]), pack_bf16(o2[6], o2[7]));
.LBB0_568:
	s_addk_i32 s49, 0xb0
	s_and_b32 s2, s49, 0xff0
	v_or_b32_e32 v18, s2, v214
	s_ashr_i32 s2, s49, 7
	s_andn2_b32 s2, s2, 31
	s_add_i32 s2, s2, s48
	s_mul_hi_i32 s3, s2, 0x88000
	s_mul_i32 s2, s2, 0x88000
	s_add_u32 s2, s88, s2
	s_addc_u32 s3, s89, s3
	s_and_b64 vcc, exec, s[8:9]
	s_mov_b64 s[8:9], -1
	s_cbranch_vccnz .LBB0_570
	v_mul_f32_e32 v0, v15, v15
	v_fmac_f32_e32 v0, v14, v14
	v_fmac_f32_e32 v0, v16, v16
	v_fmac_f32_e32 v0, v17, v17
	v_fmac_f32_e32 v0, v10, v10
	v_fmac_f32_e32 v0, v11, v11
	v_fmac_f32_e32 v0, v12, v12
	v_fmac_f32_e32 v0, v13, v13
	v_pk_mul_f32 v[22:23], v[6:7], v[6:7]
	v_pk_mul_f32 v[20:21], v[8:9], v[8:9]
	v_add_f32_e32 v0, v22, v0
	v_add_f32_e32 v0, v23, v0
	v_add_f32_e32 v0, v20, v0
	v_add_f32_e32 v0, v21, v0
	v_pk_mul_f32 v[22:23], v[2:3], v[2:3]
	v_pk_mul_f32 v[20:21], v[4:5], v[4:5]
	v_add_f32_e32 v0, v22, v0
	v_add_f32_e32 v0, v23, v0
	v_add_f32_e32 v0, v20, v0
	v_and_b32_e32 v20, 64, v211
	v_xor_b32_e32 v19, 16, v211
	v_add_u32_e32 v20, 64, v20
	v_cmp_lt_i32_e32 vcc, v19, v20
	v_add_f32_e32 v0, v21, v0
	s_mov_b32 s8, 0x800000
	v_cndmask_b32_e32 v19, v211, v19, vcc
	v_lshlrev_b32_e32 v19, 2, v19
	ds_bpermute_b32 v19, v19, v0
	v_mov_b32_e32 v28, v14
	v_mov_b32_e32 v29, v7
	v_mov_b32_e32 v30, v74
	v_mov_b32_e32 v31, v79
	s_waitcnt lgkmcnt(0)
	v_add_f32_e32 v0, v0, v19
	v_xor_b32_e32 v19, 32, v211
	v_cmp_lt_i32_e32 vcc, v19, v20
	v_mov_b32_e32 v79, v75
	v_cndmask_b32_e64 v21, 0, v97, s[6:7]
	v_cndmask_b32_e32 v19, v211, v19, vcc
	v_lshlrev_b32_e32 v19, 2, v19
	ds_bpermute_b32 v19, v19, v0
	v_cndmask_b32_e64 v20, 1.0, v94, s[6:7]
	v_cndmask_b32_e64 v23, 1.0, v96, s[6:7]
	v_cndmask_b32_e64 v22, 0, v95, s[6:7]
	v_mov_b32_e32 v35, v23
	s_waitcnt lgkmcnt(0)
	v_add_f32_e32 v0, v0, v19
	v_fmamk_f32 v0, v0, 0x3c800000, v210
	v_mul_f32_e32 v19, 0x4b800000, v0
	v_cmp_gt_f32_e32 vcc, s8, v0
	v_mov_b32_e32 v34, v20
	v_cndmask_b32_e64 v25, 0, v101, s[6:7]
	v_cndmask_b32_e32 v0, v0, v19, vcc
	v_rsq_f32_e32 v0, v0
	v_cndmask_b32_e64 v24, 1.0, v98, s[6:7]
	v_cndmask_b32_e64 v27, 1.0, v100, s[6:7]
	v_cndmask_b32_e64 v26, 0, v99, s[6:7]
	v_mul_f32_e32 v19, 0x45800000, v0
	v_cndmask_b32_e32 v0, v0, v19, vcc
	v_mul_f32_e32 v0, v217, v0
	v_pk_mul_f32 v[28:29], v[28:29], v[0:1] op_sel_hi:[1,0]
	v_mov_b32_e32 v38, v66
	v_pk_mul_f32 v[28:29], v[30:31], v[28:29]
	v_mov_b32_e32 v30, v6
	v_mov_b32_e32 v31, v15
	v_pk_mul_f32 v[30:31], v[30:31], v[0:1] op_sel_hi:[1,0]
	v_mov_b32_e32 v36, v28
	v_pk_mul_f32 v[30:31], v[78:79], v[30:31]
	v_mov_b32_e32 v39, v71
	v_pk_mul_f32 v[32:33], v[20:21], v[30:31]
	v_mov_b32_e32 v37, v31
	v_pk_fma_f32 v[32:33], v[22:23], v[28:29], v[32:33]
	v_mov_b32_e32 v23, v21
	v_mov_b32_e32 v31, v29
	v_pk_mul_f32 v[20:21], v[22:23], v[30:31]
	v_mov_b32_e32 v22, v16
	v_mov_b32_e32 v23, v9
	v_pk_mul_f32 v[22:23], v[22:23], v[0:1] op_sel_hi:[1,0]
	v_mov_b32_e32 v28, v76
	v_mov_b32_e32 v29, v81
	v_pk_mul_f32 v[22:23], v[28:29], v[22:23]
	v_mov_b32_e32 v28, v8
	v_mov_b32_e32 v29, v17
	v_pk_mul_f32 v[28:29], v[28:29], v[0:1] op_sel_hi:[1,0]
	v_mov_b32_e32 v81, v77
	v_pk_mul_f32 v[28:29], v[80:81], v[28:29]
	v_pk_fma_f32 v[20:21], v[34:35], v[36:37], v[20:21] neg_lo:[0,0,1] neg_hi:[0,0,1]
	v_pk_mul_f32 v[30:31], v[24:25], v[28:29]
	v_mov_b32_e32 v35, v27
	v_pk_fma_f32 v[30:31], v[26:27], v[22:23], v[30:31]
	v_mov_b32_e32 v37, v29
	v_mov_b32_e32 v27, v25
	v_mov_b32_e32 v29, v23
	v_mov_b32_e32 v34, v24
	v_mov_b32_e32 v36, v22
	v_pk_mul_f32 v[22:23], v[26:27], v[28:29]
	v_mov_b32_e32 v71, v67
	v_pk_fma_f32 v[22:23], v[34:35], v[36:37], v[22:23] neg_lo:[0,0,1] neg_hi:[0,0,1]
	v_mov_b32_e32 v36, v10
	v_mov_b32_e32 v37, v3
	v_pk_mul_f32 v[36:37], v[36:37], v[0:1] op_sel_hi:[1,0]
	v_cndmask_b32_e64 v25, 0, v89, s[6:7]
	v_pk_mul_f32 v[36:37], v[38:39], v[36:37]
	v_mov_b32_e32 v38, v2
	v_mov_b32_e32 v39, v11
	v_pk_mul_f32 v[38:39], v[38:39], v[0:1] op_sel_hi:[1,0]
	v_cndmask_b32_e64 v24, 1.0, v86, s[6:7]
	v_pk_mul_f32 v[38:39], v[70:71], v[38:39]
	v_cndmask_b32_e64 v27, 1.0, v88, s[6:7]
	v_cndmask_b32_e64 v26, 0, v87, s[6:7]
	v_pk_mul_f32 v[40:41], v[24:25], v[38:39]
	v_mov_b32_e32 v43, v27
	v_pk_fma_f32 v[40:41], v[26:27], v[36:37], v[40:41]
	v_mov_b32_e32 v45, v39
	v_mov_b32_e32 v27, v25
	v_mov_b32_e32 v39, v37
	v_mov_b32_e32 v42, v24
	v_pk_mul_f32 v[24:25], v[26:27], v[38:39]
	v_mov_b32_e32 v26, v12
	v_mov_b32_e32 v27, v5
	v_mov_b32_e32 v44, v36
	v_pk_mul_f32 v[26:27], v[26:27], v[0:1] op_sel_hi:[1,0]
	v_mov_b32_e32 v36, v68
	v_mov_b32_e32 v37, v73
	v_pk_mul_f32 v[26:27], v[36:37], v[26:27]
	v_mov_b32_e32 v36, v4
	v_mov_b32_e32 v37, v13
	v_pk_mul_f32 v[36:37], v[36:37], v[0:1] op_sel_hi:[1,0]
	v_mov_b32_e32 v73, v69
	v_cndmask_b32_e64 v29, 0, v85, s[6:7]
	v_cndmask_b32_e64 v28, 1.0, v82, s[6:7]
	v_pk_mul_f32 v[36:37], v[72:73], v[36:37]
	v_cndmask_b32_e64 v35, 1.0, v84, s[6:7]
	v_cndmask_b32_e64 v34, 0, v83, s[6:7]
	v_pk_mul_f32 v[38:39], v[28:29], v[36:37]
	v_pk_fma_f32 v[24:25], v[42:43], v[44:45], v[24:25] neg_lo:[0,0,1] neg_hi:[0,0,1]
	v_pk_fma_f32 v[38:39], v[34:35], v[26:27], v[38:39]
	v_mov_b32_e32 v43, v35
	v_mov_b32_e32 v45, v37
	v_mov_b32_e32 v35, v29
	v_mov_b32_e32 v37, v27
	v_mov_b32_e32 v42, v28
	v_mov_b32_e32 v44, v26
	v_pk_mul_f32 v[26:27], v[34:35], v[36:37]
	v_lshlrev_b32_e32 v0, 7, v18
	v_pk_fma_f32 v[26:27], v[42:43], v[44:45], v[26:27] neg_lo:[0,0,1] neg_hi:[0,0,1]
	v_lshl_add_u64 v[28:29], s[2:3], 0, v[0:1]
	v_mov_b32_e32 v207, v1
	v_lshl_add_u64 v[28:29], v[28:29], 0, v[206:207]
	v_cvt_pk_bf16_f32 v20, v20, v21
	v_cvt_pk_bf16_f32 v21, v22, v23
	v_cvt_pk_bf16_f32 v22, v24, v25
	v_cvt_pk_bf16_f32 v23, v26, v27
	global_store_dwordx4 v[28:29], v[20:23], off
	s_mov_b64 s[8:9], 0
	s_nop 0
	v_cvt_pk_bf16_f32 v20, v32, v33
	v_cvt_pk_bf16_f32 v21, v30, v31
	v_cvt_pk_bf16_f32 v22, v40, v41
	v_cvt_pk_bf16_f32 v23, v38, v39
	global_store_dwordx4 v[28:29], v[20:23], off offset:64

;   DI void operator()(const f32x4 (&acc)[2][2][4][2], const Unit& u, int wr, int wc, int fr, int fq) const {
;     ...
;           float ss = 0.f;
; #pragma unroll
;           for (int bj = 0; bj < 2; ++bj)
; #pragma unroll
;             for (int n = 0; n < 2; ++n)
; #pragma unroll
;               for (int e = 0; e < 4; ++e) ss += acc[ai][bj][m][n][e] * acc[ai][bj][m][n][e];
;           ss += __shfl_xor(ss, 16);
;           ss += __shfl_xor(ss, 32);
;           const float rinv = rsqrtf(ss * (1.f / 64.f) + EPSV);
;           float o1[8], o2[8];
; #pragma unroll
;           for (int n = 0; n < 2; ++n) {
;             f32x4 cs0 = (f32x4){1.f, 0.f, 1.f, 0.f}, cs1 = cs0;
;             if (ropeT) { cs0 = csr[m & 1][n][0]; cs1 = csr[m & 1][n][1]; }
; #pragma unroll
;             for (int e = 0; e < 4; ++e) {
;               float x1 = acc[ai][0][m][n][e] * (rinv * qs) * g4[0][n][e];
;               float x2 = acc[ai][1][m][n][e] * (rinv * qs) * g4[1][n][e];
;               float c = (e < 2) ? cs0[2 * e] : cs1[2 * (e - 2)], s = (e < 2) ? cs0[2 * e + 1] : cs1[2 * (e - 2) + 1];
;               o1[n * 4 + e] = x1 * c - x2 * s;
;               o2[n * 4 + e] = x2 * c + x1 * s;
;             }
;           }
;           u16* dst = base + (size_t)pos * 64 + 8 * fq;
;           *(uint4*)(dst) = make_uint4(pack_bf16(o1[0], o1[1]), pack_bf16(o1[2], o1[3]), pack_bf16(o1[4], o1[5]), pack_bf16(o1[6], o1[7]));
;           *(uint4*)(dst + 32) = make_uint4(pack_bf16(o2[0], o2[1]), pack_bf16(o2[2], o2[3]), pack_bf16(o2[4], o2[5]), pack_bf16(o2[6], o2[7]));
.LBB0_845:
	v_or_b32_e32 v130, 0x1010, v152
	s_and_b64 vcc, exec, s[4:5]
	s_mov_b64 s[2:3], -1
	s_movk_i32 s28, 0x4000
	s_cbranch_vccnz .LBB0_851
	v_mul_f32_e32 v0, v127, v127
	v_fmac_f32_e32 v0, v126, v126
	v_fmac_f32_e32 v0, v128, v128
	v_fmac_f32_e32 v0, v129, v129
	v_fmac_f32_e32 v0, v122, v122
	v_fmac_f32_e32 v0, v123, v123
	v_fmac_f32_e32 v0, v124, v124
	v_fmac_f32_e32 v0, v125, v125
	v_pk_mul_f32 v[134:135], v[118:119], v[118:119]
	v_pk_mul_f32 v[132:133], v[120:121], v[120:121]
	v_add_f32_e32 v0, v134, v0
	v_add_f32_e32 v0, v135, v0
	v_add_f32_e32 v0, v132, v0
	v_add_f32_e32 v0, v133, v0
	v_pk_mul_f32 v[134:135], v[114:115], v[114:115]
	v_pk_mul_f32 v[132:133], v[116:117], v[116:117]
	v_add_f32_e32 v0, v134, v0
	v_add_f32_e32 v0, v135, v0
	v_add_f32_e32 v0, v132, v0
	v_and_b32_e32 v132, 64, v211
	v_xor_b32_e32 v131, 16, v211
	v_add_u32_e32 v132, 64, v132
	v_cmp_lt_i32_e32 vcc, v131, v132
	v_add_f32_e32 v0, v133, v0
	v_mov_b32_e32 v147, v1
	v_cndmask_b32_e32 v131, v211, v131, vcc
	v_lshlrev_b32_e32 v131, 2, v131
	ds_bpermute_b32 v131, v131, v0
	s_waitcnt lgkmcnt(0)
	v_add_f32_e32 v0, v0, v131
	v_xor_b32_e32 v131, 32, v211
	v_cmp_lt_i32_e32 vcc, v131, v132
	s_nop 1
	v_cndmask_b32_e32 v131, v211, v131, vcc
	v_lshlrev_b32_e32 v131, 2, v131
	ds_bpermute_b32 v131, v131, v0
	s_waitcnt lgkmcnt(0)
	v_add_f32_e32 v0, v0, v131
	v_fmamk_f32 v0, v0, 0x3c800000, v210
	v_mul_f32_e32 v131, 0x4b800000, v0
	v_cmp_gt_f32_e32 vcc, s11, v0
	s_nop 1
	v_cndmask_b32_e32 v0, v0, v131, vcc
	v_rsq_f32_e32 v0, v0
	s_nop 0
	v_mul_f32_e32 v131, 0x45800000, v0
	v_cndmask_b32_e32 v0, v0, v131, vcc
	v_mul_f32_e32 v0, v151, v0
	v_pk_mul_f32 v[132:133], v[118:119], v[0:1] op_sel_hi:[1,0]
	v_pk_mul_f32 v[134:135], v[126:127], v[0:1] op_sel_hi:[1,0]
	v_pk_mul_f32 v[132:133], v[94:95], v[132:133]
	v_pk_mul_f32 v[134:135], v[90:91], v[134:135]
	v_pk_mul_f32 v[138:139], v[128:129], v[0:1] op_sel_hi:[1,0]
	v_pk_fma_f32 v[136:137], v[134:135], 0, v[132:133] op_sel_hi:[1,0,1]
	v_pk_fma_f32 v[132:133], v[132:133], 0, v[134:135] op_sel_hi:[1,0,1] neg_lo:[1,0,0] neg_hi:[1,0,0]
	v_pk_mul_f32 v[134:135], v[120:121], v[0:1] op_sel_hi:[1,0]
	v_pk_mul_f32 v[138:139], v[92:93], v[138:139]
	v_pk_mul_f32 v[134:135], v[96:97], v[134:135]
	v_pk_mul_f32 v[142:143], v[122:123], v[0:1] op_sel_hi:[1,0]
	v_pk_fma_f32 v[140:141], v[138:139], 0, v[134:135] op_sel_hi:[1,0,1]
	v_pk_fma_f32 v[134:135], v[134:135], 0, v[138:139] op_sel_hi:[1,0,1] neg_lo:[1,0,0] neg_hi:[1,0,0]
	v_pk_mul_f32 v[138:139], v[114:115], v[0:1] op_sel_hi:[1,0]
	v_pk_mul_f32 v[142:143], v[82:83], v[142:143]
	v_pk_mul_f32 v[138:139], v[86:87], v[138:139]
	v_pk_mul_f32 v[154:155], v[124:125], v[0:1] op_sel_hi:[1,0]
	v_pk_fma_f32 v[144:145], v[142:143], 0, v[138:139] op_sel_hi:[1,0,1]
	v_pk_fma_f32 v[138:139], v[138:139], 0, v[142:143] op_sel_hi:[1,0,1] neg_lo:[1,0,0] neg_hi:[1,0,0]
	v_pk_mul_f32 v[142:143], v[116:117], v[0:1] op_sel_hi:[1,0]
	v_pk_mul_f32 v[154:155], v[84:85], v[154:155]
	v_pk_mul_f32 v[142:143], v[88:89], v[142:143]
	v_lshlrev_b32_e32 v0, 7, v130
	v_pk_fma_f32 v[156:157], v[154:155], 0, v[142:143] op_sel_hi:[1,0,1]
	v_pk_fma_f32 v[142:143], v[142:143], 0, v[154:155] op_sel_hi:[1,0,1] neg_lo:[1,0,0] neg_hi:[1,0,0]
	v_lshl_add_u64 v[154:155], s[0:1], 0, v[0:1]
	v_lshl_add_u64 v[154:155], v[154:155], 0, v[146:147]
	v_cvt_pk_bf16_f32 v132, v132, v133
	v_cvt_pk_bf16_f32 v133, v134, v135
	v_cvt_pk_bf16_f32 v134, v138, v139
	v_cvt_pk_bf16_f32 v135, v142, v143
	global_store_dwordx4 v[154:155], v[132:135], off
	s_nop 1
	v_cvt_pk_bf16_f32 v132, v136, v137
	v_cvt_pk_bf16_f32 v133, v140, v141
	v_cvt_pk_bf16_f32 v134, v144, v145
	v_cvt_pk_bf16_f32 v135, v156, v157
	global_store_dwordx4 v[154:155], v[132:135], off offset:64
	s_cbranch_execz .LBB0_852

;   DI void operator()(const f32x4 (&acc)[2][2][4][2], const Unit& u, int wr, int wc, int fr, int fq) const {
;     ...
;           float ss = 0.f;
; #pragma unroll
;           for (int bj = 0; bj < 2; ++bj)
; #pragma unroll
;             for (int n = 0; n < 2; ++n)
; #pragma unroll
;               for (int e = 0; e < 4; ++e) ss += acc[ai][bj][m][n][e] * acc[ai][bj][m][n][e];
;           ss += __shfl_xor(ss, 16);
;           ss += __shfl_xor(ss, 32);
;           const float rinv = rsqrtf(ss * (1.f / 64.f) + EPSV);
;           float o1[8], o2[8];
; #pragma unroll
;           for (int n = 0; n < 2; ++n) {
;             f32x4 cs0 = (f32x4){1.f, 0.f, 1.f, 0.f}, cs1 = cs0;
;             if (ropeT) { cs0 = csr[m & 1][n][0]; cs1 = csr[m & 1][n][1]; }
; #pragma unroll
;             for (int e = 0; e < 4; ++e) {
;               float x1 = acc[ai][0][m][n][e] * (rinv * qs) * g4[0][n][e];
;               float x2 = acc[ai][1][m][n][e] * (rinv * qs) * g4[1][n][e];
;               float c = (e < 2) ? cs0[2 * e] : cs1[2 * (e - 2)], s = (e < 2) ? cs0[2 * e + 1] : cs1[2 * (e - 2) + 1];
;               o1[n * 4 + e] = x1 * c - x2 * s;
;               o2[n * 4 + e] = x2 * c + x1 * s;
;             }
;           }
;           u16* dst = base + (size_t)pos * 64 + 8 * fq;
;           *(uint4*)(dst) = make_uint4(pack_bf16(o1[0], o1[1]), pack_bf16(o1[2], o1[3]), pack_bf16(o1[4], o1[5]), pack_bf16(o1[6], o1[7]));
;           *(uint4*)(dst + 32) = make_uint4(pack_bf16(o2[0], o2[1]), pack_bf16(o2[2], o2[3]), pack_bf16(o2[4], o2[5]), pack_bf16(o2[6], o2[7]));
.LBB0_848:
	v_mul_f32_e32 v0, v111, v111
	v_fmac_f32_e32 v0, v110, v110
	v_fmac_f32_e32 v0, v112, v112
	v_fmac_f32_e32 v0, v113, v113
	v_fmac_f32_e32 v0, v106, v106
	v_fmac_f32_e32 v0, v107, v107
	v_fmac_f32_e32 v0, v108, v108
	v_fmac_f32_e32 v0, v109, v109
	v_pk_mul_f32 v[118:119], v[102:103], v[102:103]
	v_pk_mul_f32 v[116:117], v[104:105], v[104:105]
	v_add_f32_e32 v0, v118, v0
	v_add_f32_e32 v0, v119, v0
	v_add_f32_e32 v0, v116, v0
	v_add_f32_e32 v0, v117, v0
	v_pk_mul_f32 v[118:119], v[98:99], v[98:99]
	v_pk_mul_f32 v[116:117], v[100:101], v[100:101]
	v_add_f32_e32 v0, v118, v0
	v_add_f32_e32 v0, v119, v0
	v_add_f32_e32 v0, v116, v0
	v_and_b32_e32 v116, 64, v211
	v_xor_b32_e32 v115, 16, v211
	v_add_u32_e32 v116, 64, v116
	v_cmp_lt_i32_e32 vcc, v115, v116
	v_add_f32_e32 v0, v117, v0
	v_mov_b32_e32 v147, v1
	v_cndmask_b32_e32 v115, v211, v115, vcc
	v_lshlrev_b32_e32 v115, 2, v115
	ds_bpermute_b32 v115, v115, v0
	s_waitcnt lgkmcnt(0)
	v_add_f32_e32 v0, v0, v115
	v_xor_b32_e32 v115, 32, v211
	v_cmp_lt_i32_e32 vcc, v115, v116
	s_nop 1
	v_cndmask_b32_e32 v115, v211, v115, vcc
	v_lshlrev_b32_e32 v115, 2, v115
	ds_bpermute_b32 v115, v115, v0
	s_waitcnt lgkmcnt(0)
	v_add_f32_e32 v0, v0, v115
	v_fmamk_f32 v0, v0, 0x3c800000, v210
	v_mul_f32_e32 v115, 0x4b800000, v0
	v_cmp_gt_f32_e32 vcc, s11, v0
	s_nop 1
	v_cndmask_b32_e32 v0, v0, v115, vcc
	v_rsq_f32_e32 v0, v0
	s_nop 0
	v_mul_f32_e32 v115, 0x45800000, v0
	v_cndmask_b32_e32 v0, v0, v115, vcc
	v_mul_f32_e32 v0, v151, v0
	v_pk_mul_f32 v[116:117], v[102:103], v[0:1] op_sel_hi:[1,0]
	v_pk_mul_f32 v[118:119], v[110:111], v[0:1] op_sel_hi:[1,0]
	v_pk_mul_f32 v[116:117], v[94:95], v[116:117]
	v_pk_mul_f32 v[118:119], v[90:91], v[118:119]
	v_pk_mul_f32 v[122:123], v[112:113], v[0:1] op_sel_hi:[1,0]
	v_pk_fma_f32 v[120:121], v[118:119], 0, v[116:117] op_sel_hi:[1,0,1]
	v_pk_fma_f32 v[116:117], v[116:117], 0, v[118:119] op_sel_hi:[1,0,1] neg_lo:[1,0,0] neg_hi:[1,0,0]
	v_pk_mul_f32 v[118:119], v[104:105], v[0:1] op_sel_hi:[1,0]
	v_pk_mul_f32 v[122:123], v[92:93], v[122:123]
	v_pk_mul_f32 v[118:119], v[96:97], v[118:119]
	v_pk_mul_f32 v[126:127], v[106:107], v[0:1] op_sel_hi:[1,0]
	v_pk_fma_f32 v[124:125], v[122:123], 0, v[118:119] op_sel_hi:[1,0,1]
	v_pk_fma_f32 v[118:119], v[118:119], 0, v[122:123] op_sel_hi:[1,0,1] neg_lo:[1,0,0] neg_hi:[1,0,0]
	v_pk_mul_f32 v[122:123], v[98:99], v[0:1] op_sel_hi:[1,0]
	v_pk_mul_f32 v[126:127], v[82:83], v[126:127]
	v_pk_mul_f32 v[122:123], v[86:87], v[122:123]
	v_pk_mul_f32 v[130:131], v[108:109], v[0:1] op_sel_hi:[1,0]
	v_pk_fma_f32 v[128:129], v[126:127], 0, v[122:123] op_sel_hi:[1,0,1]
	v_pk_fma_f32 v[122:123], v[122:123], 0, v[126:127] op_sel_hi:[1,0,1] neg_lo:[1,0,0] neg_hi:[1,0,0]
	v_pk_mul_f32 v[126:127], v[100:101], v[0:1] op_sel_hi:[1,0]
	v_pk_mul_f32 v[130:131], v[84:85], v[130:131]
	v_pk_mul_f32 v[126:127], v[88:89], v[126:127]
	v_lshlrev_b32_e32 v0, 7, v114
	v_pk_fma_f32 v[132:133], v[130:131], 0, v[126:127] op_sel_hi:[1,0,1]
	v_pk_fma_f32 v[126:127], v[126:127], 0, v[130:131] op_sel_hi:[1,0,1] neg_lo:[1,0,0] neg_hi:[1,0,0]
	v_lshl_add_u64 v[130:131], s[0:1], 0, v[0:1]
	v_lshl_add_u64 v[130:131], v[130:131], 0, v[146:147]
	v_cvt_pk_bf16_f32 v116, v116, v117
	v_cvt_pk_bf16_f32 v117, v118, v119
	v_cvt_pk_bf16_f32 v118, v122, v123
	v_cvt_pk_bf16_f32 v119, v126, v127
	global_store_dwordx4 v[130:131], v[116:119], off
	s_nop 1
	v_cvt_pk_bf16_f32 v116, v120, v121
	v_cvt_pk_bf16_f32 v117, v124, v125
	v_cvt_pk_bf16_f32 v118, v128, v129
	v_cvt_pk_bf16_f32 v119, v132, v133
	global_store_dwordx4 v[130:131], v[116:119], off offset:64
	s_cbranch_execz .LBB0_854

;   DI void operator()(const f32x4 (&acc)[2][2][4][2], const Unit& u, int wr, int wc, int fr, int fq) const {
;     ...
;           float ss = 0.f;
; #pragma unroll
;           for (int bj = 0; bj < 2; ++bj)
; #pragma unroll
;             for (int n = 0; n < 2; ++n)
; #pragma unroll
;               for (int e = 0; e < 4; ++e) ss += acc[ai][bj][m][n][e] * acc[ai][bj][m][n][e];
;           ss += __shfl_xor(ss, 16);
;           ss += __shfl_xor(ss, 32);
;           const float rinv = rsqrtf(ss * (1.f / 64.f) + EPSV);
;           float o1[8], o2[8];
; #pragma unroll
;           for (int n = 0; n < 2; ++n) {
;             f32x4 cs0 = (f32x4){1.f, 0.f, 1.f, 0.f}, cs1 = cs0;
;             if (ropeT) { cs0 = csr[m & 1][n][0]; cs1 = csr[m & 1][n][1]; }
; #pragma unroll
;             for (int e = 0; e < 4; ++e) {
;               float x1 = acc[ai][0][m][n][e] * (rinv * qs) * g4[0][n][e];
;               float x2 = acc[ai][1][m][n][e] * (rinv * qs) * g4[1][n][e];
;               float c = (e < 2) ? cs0[2 * e] : cs1[2 * (e - 2)], s = (e < 2) ? cs0[2 * e + 1] : cs1[2 * (e - 2) + 1];
;               o1[n * 4 + e] = x1 * c - x2 * s;
;               o2[n * 4 + e] = x2 * c + x1 * s;
;             }
;           }
;           u16* dst = base + (size_t)pos * 64 + 8 * fq;
;           *(uint4*)(dst) = make_uint4(pack_bf16(o1[0], o1[1]), pack_bf16(o1[2], o1[3]), pack_bf16(o1[4], o1[5]), pack_bf16(o1[6], o1[7]));
;           *(uint4*)(dst + 32) = make_uint4(pack_bf16(o2[0], o2[1]), pack_bf16(o2[2], o2[3]), pack_bf16(o2[4], o2[5]), pack_bf16(o2[6], o2[7]));
.LBB0_850:
	v_mul_f32_e32 v0, v79, v79
	v_fmac_f32_e32 v0, v78, v78
	v_fmac_f32_e32 v0, v80, v80
	v_fmac_f32_e32 v0, v81, v81
	v_fmac_f32_e32 v0, v74, v74
	v_fmac_f32_e32 v0, v75, v75
	v_fmac_f32_e32 v0, v76, v76
	v_fmac_f32_e32 v0, v77, v77
	v_pk_mul_f32 v[102:103], v[70:71], v[70:71]
	v_pk_mul_f32 v[100:101], v[72:73], v[72:73]
	v_add_f32_e32 v0, v102, v0
	v_add_f32_e32 v0, v103, v0
	v_add_f32_e32 v0, v100, v0
	v_add_f32_e32 v0, v101, v0
	v_pk_mul_f32 v[102:103], v[66:67], v[66:67]
	v_pk_mul_f32 v[100:101], v[68:69], v[68:69]
	v_add_f32_e32 v0, v102, v0
	v_add_f32_e32 v0, v103, v0
	v_add_f32_e32 v0, v100, v0
	v_and_b32_e32 v100, 64, v211
	v_xor_b32_e32 v99, 16, v211
	v_add_u32_e32 v100, 64, v100
	v_cmp_lt_i32_e32 vcc, v99, v100
	v_add_f32_e32 v0, v101, v0
	v_mov_b32_e32 v147, v1
	v_cndmask_b32_e32 v99, v211, v99, vcc
	v_lshlrev_b32_e32 v99, 2, v99
	ds_bpermute_b32 v99, v99, v0
	s_waitcnt lgkmcnt(0)
	v_add_f32_e32 v0, v0, v99
	v_xor_b32_e32 v99, 32, v211
	v_cmp_lt_i32_e32 vcc, v99, v100
	s_nop 1
	v_cndmask_b32_e32 v99, v211, v99, vcc
	v_lshlrev_b32_e32 v99, 2, v99
	ds_bpermute_b32 v99, v99, v0
	s_waitcnt lgkmcnt(0)
	v_add_f32_e32 v0, v0, v99
	v_fmamk_f32 v0, v0, 0x3c800000, v210
	v_mul_f32_e32 v99, 0x4b800000, v0
	v_cmp_gt_f32_e32 vcc, s11, v0
	s_nop 1
	v_cndmask_b32_e32 v0, v0, v99, vcc
	v_rsq_f32_e32 v0, v0
	s_nop 0
	v_mul_f32_e32 v99, 0x45800000, v0
	v_cndmask_b32_e32 v0, v0, v99, vcc
	v_mul_f32_e32 v0, v151, v0
	v_pk_mul_f32 v[100:101], v[70:71], v[0:1] op_sel_hi:[1,0]
	v_pk_mul_f32 v[102:103], v[78:79], v[0:1] op_sel_hi:[1,0]
	v_pk_mul_f32 v[100:101], v[94:95], v[100:101]
	v_pk_mul_f32 v[102:103], v[90:91], v[102:103]
	v_pk_mul_f32 v[106:107], v[80:81], v[0:1] op_sel_hi:[1,0]
	v_pk_fma_f32 v[104:105], v[102:103], 0, v[100:101] op_sel_hi:[1,0,1]
	v_pk_fma_f32 v[100:101], v[100:101], 0, v[102:103] op_sel_hi:[1,0,1] neg_lo:[1,0,0] neg_hi:[1,0,0]
	v_pk_mul_f32 v[102:103], v[72:73], v[0:1] op_sel_hi:[1,0]
	v_pk_mul_f32 v[106:107], v[92:93], v[106:107]
	v_pk_mul_f32 v[102:103], v[96:97], v[102:103]
	v_pk_mul_f32 v[110:111], v[74:75], v[0:1] op_sel_hi:[1,0]
	v_pk_fma_f32 v[108:109], v[106:107], 0, v[102:103] op_sel_hi:[1,0,1]
	v_pk_fma_f32 v[102:103], v[102:103], 0, v[106:107] op_sel_hi:[1,0,1] neg_lo:[1,0,0] neg_hi:[1,0,0]
	v_pk_mul_f32 v[106:107], v[66:67], v[0:1] op_sel_hi:[1,0]
	v_pk_mul_f32 v[110:111], v[82:83], v[110:111]
	v_pk_mul_f32 v[106:107], v[86:87], v[106:107]
	v_pk_mul_f32 v[114:115], v[76:77], v[0:1] op_sel_hi:[1,0]
	v_pk_fma_f32 v[112:113], v[110:111], 0, v[106:107] op_sel_hi:[1,0,1]
	v_pk_fma_f32 v[106:107], v[106:107], 0, v[110:111] op_sel_hi:[1,0,1] neg_lo:[1,0,0] neg_hi:[1,0,0]
	v_pk_mul_f32 v[110:111], v[68:69], v[0:1] op_sel_hi:[1,0]
	v_pk_mul_f32 v[114:115], v[84:85], v[114:115]
	v_pk_mul_f32 v[110:111], v[88:89], v[110:111]
	v_lshlrev_b32_e32 v0, 7, v98
	v_pk_fma_f32 v[116:117], v[114:115], 0, v[110:111] op_sel_hi:[1,0,1]
	v_pk_fma_f32 v[110:111], v[110:111], 0, v[114:115] op_sel_hi:[1,0,1] neg_lo:[1,0,0] neg_hi:[1,0,0]
	v_lshl_add_u64 v[114:115], s[0:1], 0, v[0:1]
	v_lshl_add_u64 v[114:115], v[114:115], 0, v[146:147]
	v_cvt_pk_bf16_f32 v100, v100, v101
	v_cvt_pk_bf16_f32 v101, v102, v103
	v_cvt_pk_bf16_f32 v102, v106, v107
	v_cvt_pk_bf16_f32 v103, v110, v111
	global_store_dwordx4 v[114:115], v[100:103], off
	s_nop 1
	v_cvt_pk_bf16_f32 v100, v104, v105
	v_cvt_pk_bf16_f32 v101, v108, v109
	v_cvt_pk_bf16_f32 v102, v112, v113
	v_cvt_pk_bf16_f32 v103, v116, v117
	global_store_dwordx4 v[114:115], v[100:103], off offset:64
	s_cbranch_execz .LBB0_856
	s_branch .LBB0_857

;   DI void operator()(const f32x4 (&acc)[2][2][4][2], const Unit& u, int wr, int wc, int fr, int fq) const {
;     ...
;           float ss = 0.f;
; #pragma unroll
;           for (int bj = 0; bj < 2; ++bj)
; #pragma unroll
;             for (int n = 0; n < 2; ++n)
; #pragma unroll
;               for (int e = 0; e < 4; ++e) ss += acc[ai][bj][m][n][e] * acc[ai][bj][m][n][e];
;           ss += __shfl_xor(ss, 16);
;           ss += __shfl_xor(ss, 32);
;           const float rinv = rsqrtf(ss * (1.f / 64.f) + EPSV);
;           float o1[8], o2[8];
; #pragma unroll
;           for (int n = 0; n < 2; ++n) {
;             f32x4 cs0 = (f32x4){1.f, 0.f, 1.f, 0.f}, cs1 = cs0;
;             if (ropeT) { cs0 = csr[m & 1][n][0]; cs1 = csr[m & 1][n][1]; }
; #pragma unroll
;             for (int e = 0; e < 4; ++e) {
;               float x1 = acc[ai][0][m][n][e] * (rinv * qs) * g4[0][n][e];
;               float x2 = acc[ai][1][m][n][e] * (rinv * qs) * g4[1][n][e];
;               float c = (e < 2) ? cs0[2 * e] : cs1[2 * (e - 2)], s = (e < 2) ? cs0[2 * e + 1] : cs1[2 * (e - 2) + 1];
;               o1[n * 4 + e] = x1 * c - x2 * s;
;               o2[n * 4 + e] = x2 * c + x1 * s;
;             }
;           }
;           u16* dst = base + (size_t)pos * 64 + 8 * fq;
;           *(uint4*)(dst) = make_uint4(pack_bf16(o1[0], o1[1]), pack_bf16(o1[2], o1[3]), pack_bf16(o1[4], o1[5]), pack_bf16(o1[6], o1[7]));
;           *(uint4*)(dst + 32) = make_uint4(pack_bf16(o2[0], o2[1]), pack_bf16(o2[2], o2[3]), pack_bf16(o2[4], o2[5]), pack_bf16(o2[6], o2[7]));
.LBB0_857:
	s_add_i32 s0, s15, 0x80
	s_add_i32 s1, s0, s10
	s_and_b32 s0, s0, 0xc0
	v_or_b32_e32 v0, s0, v150
	s_ashr_i32 s0, s1, 3
	s_andn2_b32 s0, s0, 31
	s_add_i32 s0, s0, s8
	s_mul_hi_i32 s1, s0, 0x88000
	s_mul_i32 s0, s0, 0x88000
	s_add_u32 s0, s88, s0
	v_or_b32_e32 v66, 0x1000, v0
	s_addc_u32 s1, s89, s1
	s_and_b64 vcc, exec, s[4:5]
	s_mov_b64 s[2:3], -1
	s_cbranch_vccnz .LBB0_859
	v_mul_f32_e32 v0, v63, v63
	v_fmac_f32_e32 v0, v62, v62
	v_fmac_f32_e32 v0, v64, v64
	v_fmac_f32_e32 v0, v65, v65
	v_fmac_f32_e32 v0, v58, v58
	v_fmac_f32_e32 v0, v59, v59
	v_fmac_f32_e32 v0, v60, v60
	v_fmac_f32_e32 v0, v61, v61
	v_pk_mul_f32 v[70:71], v[54:55], v[54:55]
	v_pk_mul_f32 v[68:69], v[56:57], v[56:57]
	v_add_f32_e32 v0, v70, v0
	v_add_f32_e32 v0, v71, v0
	v_add_f32_e32 v0, v68, v0
	v_add_f32_e32 v0, v69, v0
	v_pk_mul_f32 v[70:71], v[50:51], v[50:51]
	v_pk_mul_f32 v[68:69], v[52:53], v[52:53]
	v_add_f32_e32 v0, v70, v0
	v_add_f32_e32 v0, v71, v0
	v_add_f32_e32 v0, v68, v0
	v_and_b32_e32 v68, 64, v211
	v_xor_b32_e32 v67, 16, v211
	v_add_u32_e32 v68, 64, v68
	v_cmp_lt_i32_e32 vcc, v67, v68
	v_add_f32_e32 v0, v69, v0
	v_mov_b32_e32 v147, v1
	v_cndmask_b32_e32 v67, v211, v67, vcc
	v_lshlrev_b32_e32 v67, 2, v67
	ds_bpermute_b32 v67, v67, v0
	s_mov_b64 s[2:3], 0
	s_waitcnt lgkmcnt(0)
	v_add_f32_e32 v0, v0, v67
	v_xor_b32_e32 v67, 32, v211
	v_cmp_lt_i32_e32 vcc, v67, v68
	s_nop 1
	v_cndmask_b32_e32 v67, v211, v67, vcc
	v_lshlrev_b32_e32 v67, 2, v67
	ds_bpermute_b32 v67, v67, v0
	s_waitcnt lgkmcnt(0)
	v_add_f32_e32 v0, v0, v67
	v_fmamk_f32 v0, v0, 0x3c800000, v210
	v_mul_f32_e32 v67, 0x4b800000, v0
	v_cmp_gt_f32_e32 vcc, s11, v0
	s_nop 1
	v_cndmask_b32_e32 v0, v0, v67, vcc
	v_rsq_f32_e32 v0, v0
	s_nop 0
	v_mul_f32_e32 v67, 0x45800000, v0
	v_cndmask_b32_e32 v0, v0, v67, vcc
	v_mul_f32_e32 v0, v151, v0
	v_pk_mul_f32 v[68:69], v[54:55], v[0:1] op_sel_hi:[1,0]
	v_pk_mul_f32 v[70:71], v[62:63], v[0:1] op_sel_hi:[1,0]
	v_pk_mul_f32 v[68:69], v[94:95], v[68:69]
	v_pk_mul_f32 v[70:71], v[90:91], v[70:71]
	v_pk_mul_f32 v[74:75], v[64:65], v[0:1] op_sel_hi:[1,0]
	v_pk_fma_f32 v[72:73], v[70:71], 0, v[68:69] op_sel_hi:[1,0,1]
	v_pk_fma_f32 v[68:69], v[68:69], 0, v[70:71] op_sel_hi:[1,0,1] neg_lo:[1,0,0] neg_hi:[1,0,0]
	v_pk_mul_f32 v[70:71], v[56:57], v[0:1] op_sel_hi:[1,0]
	v_pk_mul_f32 v[74:75], v[92:93], v[74:75]
	v_pk_mul_f32 v[70:71], v[96:97], v[70:71]
	v_pk_mul_f32 v[78:79], v[58:59], v[0:1] op_sel_hi:[1,0]
	v_pk_fma_f32 v[76:77], v[74:75], 0, v[70:71] op_sel_hi:[1,0,1]
	v_pk_fma_f32 v[70:71], v[70:71], 0, v[74:75] op_sel_hi:[1,0,1] neg_lo:[1,0,0] neg_hi:[1,0,0]
	v_pk_mul_f32 v[74:75], v[50:51], v[0:1] op_sel_hi:[1,0]
	v_pk_mul_f32 v[78:79], v[82:83], v[78:79]
	v_pk_mul_f32 v[74:75], v[86:87], v[74:75]
	v_pk_mul_f32 v[98:99], v[60:61], v[0:1] op_sel_hi:[1,0]
	v_pk_fma_f32 v[80:81], v[78:79], 0, v[74:75] op_sel_hi:[1,0,1]
	v_pk_fma_f32 v[74:75], v[74:75], 0, v[78:79] op_sel_hi:[1,0,1] neg_lo:[1,0,0] neg_hi:[1,0,0]
	v_pk_mul_f32 v[78:79], v[52:53], v[0:1] op_sel_hi:[1,0]
	v_pk_mul_f32 v[98:99], v[84:85], v[98:99]
	v_pk_mul_f32 v[78:79], v[88:89], v[78:79]
	v_lshlrev_b32_e32 v0, 7, v66
	v_pk_fma_f32 v[100:101], v[98:99], 0, v[78:79] op_sel_hi:[1,0,1]
	v_pk_fma_f32 v[78:79], v[78:79], 0, v[98:99] op_sel_hi:[1,0,1] neg_lo:[1,0,0] neg_hi:[1,0,0]
	v_lshl_add_u64 v[98:99], s[0:1], 0, v[0:1]
	v_lshl_add_u64 v[98:99], v[98:99], 0, v[146:147]
	v_cvt_pk_bf16_f32 v68, v68, v69
	v_cvt_pk_bf16_f32 v69, v70, v71
	v_cvt_pk_bf16_f32 v70, v74, v75
	v_cvt_pk_bf16_f32 v71, v78, v79
	global_store_dwordx4 v[98:99], v[68:71], off
	s_nop 1
	v_cvt_pk_bf16_f32 v68, v72, v73
	v_cvt_pk_bf16_f32 v69, v76, v77
	v_cvt_pk_bf16_f32 v70, v80, v81
	v_cvt_pk_bf16_f32 v71, v100, v101
	global_store_dwordx4 v[98:99], v[68:71], off offset:64

;   DI void operator()(const f32x4 (&acc)[2][2][4][2], const Unit& u, int wr, int wc, int fr, int fq) const {
;     ...
;           float ss = 0.f;
; #pragma unroll
;           for (int bj = 0; bj < 2; ++bj)
; #pragma unroll
;             for (int n = 0; n < 2; ++n)
; #pragma unroll
;               for (int e = 0; e < 4; ++e) ss += acc[ai][bj][m][n][e] * acc[ai][bj][m][n][e];
;           ss += __shfl_xor(ss, 16);
;           ss += __shfl_xor(ss, 32);
;           const float rinv = rsqrtf(ss * (1.f / 64.f) + EPSV);
;           float o1[8], o2[8];
; #pragma unroll
;           for (int n = 0; n < 2; ++n) {
;             f32x4 cs0 = (f32x4){1.f, 0.f, 1.f, 0.f}, cs1 = cs0;
;             if (ropeT) { cs0 = csr[m & 1][n][0]; cs1 = csr[m & 1][n][1]; }
; #pragma unroll
;             for (int e = 0; e < 4; ++e) {
;               float x1 = acc[ai][0][m][n][e] * (rinv * qs) * g4[0][n][e];
;               float x2 = acc[ai][1][m][n][e] * (rinv * qs) * g4[1][n][e];
;               float c = (e < 2) ? cs0[2 * e] : cs1[2 * (e - 2)], s = (e < 2) ? cs0[2 * e + 1] : cs1[2 * (e - 2) + 1];
;               o1[n * 4 + e] = x1 * c - x2 * s;
;               o2[n * 4 + e] = x2 * c + x1 * s;
;             }
;           }
;           u16* dst = base + (size_t)pos * 64 + 8 * fq;
;           *(uint4*)(dst) = make_uint4(pack_bf16(o1[0], o1[1]), pack_bf16(o1[2], o1[3]), pack_bf16(o1[4], o1[5]), pack_bf16(o1[6], o1[7]));
;           *(uint4*)(dst + 32) = make_uint4(pack_bf16(o2[0], o2[1]), pack_bf16(o2[2], o2[3]), pack_bf16(o2[4], o2[5]), pack_bf16(o2[6], o2[7]));
.LBB0_861:
	s_add_i32 s0, s15, 0x90
	s_add_i32 s1, s0, s10
	s_and_b32 s0, s0, 0xd0
	v_or_b32_e32 v0, s0, v150
	s_ashr_i32 s0, s1, 3
	s_andn2_b32 s0, s0, 31
	s_add_i32 s0, s0, s8
	s_mul_hi_i32 s1, s0, 0x88000
	s_mul_i32 s0, s0, 0x88000
	s_add_u32 s0, s88, s0
	v_or_b32_e32 v50, 0x1000, v0
	s_addc_u32 s1, s89, s1
	s_and_b64 vcc, exec, s[4:5]
	s_mov_b64 s[2:3], -1
	s_cbranch_vccnz .LBB0_863
	v_mul_f32_e32 v0, v47, v47
	v_fmac_f32_e32 v0, v46, v46
	v_fmac_f32_e32 v0, v48, v48
	v_fmac_f32_e32 v0, v49, v49
	v_fmac_f32_e32 v0, v42, v42
	v_fmac_f32_e32 v0, v43, v43
	v_fmac_f32_e32 v0, v44, v44
	v_fmac_f32_e32 v0, v45, v45
	v_pk_mul_f32 v[54:55], v[38:39], v[38:39]
	v_pk_mul_f32 v[52:53], v[40:41], v[40:41]
	v_add_f32_e32 v0, v54, v0
	v_add_f32_e32 v0, v55, v0
	v_add_f32_e32 v0, v52, v0
	v_add_f32_e32 v0, v53, v0
	v_pk_mul_f32 v[54:55], v[34:35], v[34:35]
	v_pk_mul_f32 v[52:53], v[36:37], v[36:37]
	v_add_f32_e32 v0, v54, v0
	v_add_f32_e32 v0, v55, v0
	v_add_f32_e32 v0, v52, v0
	v_and_b32_e32 v52, 64, v211
	v_xor_b32_e32 v51, 16, v211
	v_add_u32_e32 v52, 64, v52
	v_cmp_lt_i32_e32 vcc, v51, v52
	v_add_f32_e32 v0, v53, v0
	v_mov_b32_e32 v147, v1
	v_cndmask_b32_e32 v51, v211, v51, vcc
	v_lshlrev_b32_e32 v51, 2, v51
	ds_bpermute_b32 v51, v51, v0
	s_mov_b64 s[2:3], 0
	s_waitcnt lgkmcnt(0)
	v_add_f32_e32 v0, v0, v51
	v_xor_b32_e32 v51, 32, v211
	v_cmp_lt_i32_e32 vcc, v51, v52
	s_nop 1
	v_cndmask_b32_e32 v51, v211, v51, vcc
	v_lshlrev_b32_e32 v51, 2, v51
	ds_bpermute_b32 v51, v51, v0
	s_waitcnt lgkmcnt(0)
	v_add_f32_e32 v0, v0, v51
	v_fmamk_f32 v0, v0, 0x3c800000, v210
	v_mul_f32_e32 v51, 0x4b800000, v0
	v_cmp_gt_f32_e32 vcc, s11, v0
	s_nop 1
	v_cndmask_b32_e32 v0, v0, v51, vcc
	v_rsq_f32_e32 v0, v0
	s_nop 0
	v_mul_f32_e32 v51, 0x45800000, v0
	v_cndmask_b32_e32 v0, v0, v51, vcc
	v_mul_f32_e32 v0, v151, v0
	v_pk_mul_f32 v[52:53], v[38:39], v[0:1] op_sel_hi:[1,0]
	v_pk_mul_f32 v[54:55], v[46:47], v[0:1] op_sel_hi:[1,0]
	v_pk_mul_f32 v[52:53], v[94:95], v[52:53]
	v_pk_mul_f32 v[54:55], v[90:91], v[54:55]
	v_pk_mul_f32 v[58:59], v[48:49], v[0:1] op_sel_hi:[1,0]
	v_pk_fma_f32 v[56:57], v[54:55], 0, v[52:53] op_sel_hi:[1,0,1]
	v_pk_fma_f32 v[52:53], v[52:53], 0, v[54:55] op_sel_hi:[1,0,1] neg_lo:[1,0,0] neg_hi:[1,0,0]
	v_pk_mul_f32 v[54:55], v[40:41], v[0:1] op_sel_hi:[1,0]
	v_pk_mul_f32 v[58:59], v[92:93], v[58:59]
	v_pk_mul_f32 v[54:55], v[96:97], v[54:55]
	v_pk_mul_f32 v[62:63], v[42:43], v[0:1] op_sel_hi:[1,0]
	v_pk_fma_f32 v[60:61], v[58:59], 0, v[54:55] op_sel_hi:[1,0,1]
	v_pk_fma_f32 v[54:55], v[54:55], 0, v[58:59] op_sel_hi:[1,0,1] neg_lo:[1,0,0] neg_hi:[1,0,0]
	v_pk_mul_f32 v[58:59], v[34:35], v[0:1] op_sel_hi:[1,0]
	v_pk_mul_f32 v[62:63], v[82:83], v[62:63]
	v_pk_mul_f32 v[58:59], v[86:87], v[58:59]
	v_pk_mul_f32 v[66:67], v[44:45], v[0:1] op_sel_hi:[1,0]
	v_pk_fma_f32 v[64:65], v[62:63], 0, v[58:59] op_sel_hi:[1,0,1]
	v_pk_fma_f32 v[58:59], v[58:59], 0, v[62:63] op_sel_hi:[1,0,1] neg_lo:[1,0,0] neg_hi:[1,0,0]
	v_pk_mul_f32 v[62:63], v[36:37], v[0:1] op_sel_hi:[1,0]
	v_pk_mul_f32 v[66:67], v[84:85], v[66:67]
	v_pk_mul_f32 v[62:63], v[88:89], v[62:63]
	v_lshlrev_b32_e32 v0, 7, v50
	v_pk_fma_f32 v[68:69], v[66:67], 0, v[62:63] op_sel_hi:[1,0,1]
	v_pk_fma_f32 v[62:63], v[62:63], 0, v[66:67] op_sel_hi:[1,0,1] neg_lo:[1,0,0] neg_hi:[1,0,0]
	v_lshl_add_u64 v[66:67], s[0:1], 0, v[0:1]
	v_lshl_add_u64 v[66:67], v[66:67], 0, v[146:147]
	v_cvt_pk_bf16_f32 v52, v52, v53
	v_cvt_pk_bf16_f32 v53, v54, v55
	v_cvt_pk_bf16_f32 v54, v58, v59
	v_cvt_pk_bf16_f32 v55, v62, v63
	global_store_dwordx4 v[66:67], v[52:55], off
	s_nop 1
	v_cvt_pk_bf16_f32 v52, v56, v57
	v_cvt_pk_bf16_f32 v53, v60, v61
	v_cvt_pk_bf16_f32 v54, v64, v65
	v_cvt_pk_bf16_f32 v55, v68, v69
	global_store_dwordx4 v[66:67], v[52:55], off offset:64

; DI u16 f2bf(float a) { return (u16)(pack_bf16(a, 0.f) & 0xffffu); }
;   DI void operator()(const f32x4 (&acc)[2][2][4][2], const Unit& u, int wr, int wc, int fr, int fq) const {
;     ...
;         if (rowbase == 0) { b = t >> 12; pos = t & 4095; } else { b = t >> 8; pos = 4096 + (t & 255); }
;         u16* base = qkv + (size_t)(b * 32 + chunk) * LTOT * 64;
;         if (isV) {
; #pragma unroll
;           for (int bj = 0; bj < 2; ++bj)
; #pragma unroll
;             for (int n = 0; n < 2; ++n)
; #pragma unroll
;               for (int e = 0; e < 4; ++e) {
;                 int d = 32 * bj + 8 * fq + 4 * n + e;
;                 base[(size_t)d * LTOT + pos] = f2bf(acc[ai][bj][m][n][e]);
;               }
;         } else {
;           float ss = 0.f;
; #pragma unroll
;           for (int bj = 0; bj < 2; ++bj)
; #pragma unroll
;             for (int n = 0; n < 2; ++n)
; #pragma unroll
;               for (int e = 0; e < 4; ++e) ss += acc[ai][bj][m][n][e] * acc[ai][bj][m][n][e];
;           ss += __shfl_xor(ss, 16);
;           ss += __shfl_xor(ss, 32);
;           const float rinv = rsqrtf(ss * (1.f / 64.f) + EPSV);
;           float o1[8], o2[8];
; #pragma unroll
;           for (int n = 0; n < 2; ++n) {
;             f32x4 cs0 = (f32x4){1.f, 0.f, 1.f, 0.f}, cs1 = cs0;
;             if (ropeT) { cs0 = csr[m & 1][n][0]; cs1 = csr[m & 1][n][1]; }
; #pragma unroll
;             for (int e = 0; e < 4; ++e) {
;               float x1 = acc[ai][0][m][n][e] * (rinv * qs) * g4[0][n][e];
;               float x2 = acc[ai][1][m][n][e] * (rinv * qs) * g4[1][n][e];
;               float c = (e < 2) ? cs0[2 * e] : cs1[2 * (e - 2)], s = (e < 2) ? cs0[2 * e + 1] : cs1[2 * (e - 2) + 1];
;               o1[n * 4 + e] = x1 * c - x2 * s;
;               o2[n * 4 + e] = x2 * c + x1 * s;
;             }
;           }
;           u16* dst = base + (size_t)pos * 64 + 8 * fq;
;           *(uint4*)(dst) = make_uint4(pack_bf16(o1[0], o1[1]), pack_bf16(o1[2], o1[3]), pack_bf16(o1[4], o1[5]), pack_bf16(o1[6], o1[7]));
;           *(uint4*)(dst + 32) = make_uint4(pack_bf16(o2[0], o2[1]), pack_bf16(o2[2], o2[3]), pack_bf16(o2[4], o2[5]), pack_bf16(o2[6], o2[7]));
.LBB0_865:
	s_add_i32 s0, s15, 0xa0
	s_add_i32 s1, s0, s10
	s_and_b32 s0, s0, 0xe0
	v_or_b32_e32 v0, s0, v150
	s_ashr_i32 s0, s1, 3
	s_andn2_b32 s0, s0, 31
	s_add_i32 s0, s0, s8
	s_mul_hi_i32 s1, s0, 0x88000
	s_mul_i32 s0, s0, 0x88000
	s_add_u32 s0, s88, s0
	v_or_b32_e32 v34, 0x1000, v0
	s_addc_u32 s1, s89, s1
	s_and_b64 vcc, exec, s[4:5]
	s_mov_b64 s[2:3], -1
	s_cbranch_vccnz .LBB0_867
	v_mul_f32_e32 v0, v31, v31
	v_fmac_f32_e32 v0, v30, v30
	v_fmac_f32_e32 v0, v32, v32
	v_fmac_f32_e32 v0, v33, v33
	v_fmac_f32_e32 v0, v26, v26
	v_fmac_f32_e32 v0, v27, v27
	v_fmac_f32_e32 v0, v28, v28
	v_fmac_f32_e32 v0, v29, v29
	v_pk_mul_f32 v[38:39], v[22:23], v[22:23]
	v_pk_mul_f32 v[36:37], v[24:25], v[24:25]
	v_add_f32_e32 v0, v38, v0
	v_add_f32_e32 v0, v39, v0
	v_add_f32_e32 v0, v36, v0
	v_add_f32_e32 v0, v37, v0
	v_pk_mul_f32 v[38:39], v[18:19], v[18:19]
	v_pk_mul_f32 v[36:37], v[20:21], v[20:21]
	v_add_f32_e32 v0, v38, v0
	v_add_f32_e32 v0, v39, v0
	v_add_f32_e32 v0, v36, v0
	v_and_b32_e32 v36, 64, v211
	v_xor_b32_e32 v35, 16, v211
	v_add_u32_e32 v36, 64, v36
	v_cmp_lt_i32_e32 vcc, v35, v36
	v_add_f32_e32 v0, v37, v0
	v_mov_b32_e32 v147, v1
	v_cndmask_b32_e32 v35, v211, v35, vcc
	v_lshlrev_b32_e32 v35, 2, v35
	ds_bpermute_b32 v35, v35, v0
	s_mov_b64 s[2:3], 0
	s_waitcnt lgkmcnt(0)
	v_add_f32_e32 v0, v0, v35
	v_xor_b32_e32 v35, 32, v211
	v_cmp_lt_i32_e32 vcc, v35, v36
	s_nop 1
	v_cndmask_b32_e32 v35, v211, v35, vcc
	v_lshlrev_b32_e32 v35, 2, v35
	ds_bpermute_b32 v35, v35, v0
	s_waitcnt lgkmcnt(0)
	v_add_f32_e32 v0, v0, v35
	v_fmamk_f32 v0, v0, 0x3c800000, v210
	v_mul_f32_e32 v35, 0x4b800000, v0
	v_cmp_gt_f32_e32 vcc, s11, v0
	s_nop 1
	v_cndmask_b32_e32 v0, v0, v35, vcc
	v_rsq_f32_e32 v0, v0
	s_nop 0
	v_mul_f32_e32 v35, 0x45800000, v0
	v_cndmask_b32_e32 v0, v0, v35, vcc
	v_mul_f32_e32 v0, v151, v0
	v_pk_mul_f32 v[36:37], v[22:23], v[0:1] op_sel_hi:[1,0]
	v_pk_mul_f32 v[38:39], v[30:31], v[0:1] op_sel_hi:[1,0]
	v_pk_mul_f32 v[36:37], v[94:95], v[36:37]
	v_pk_mul_f32 v[38:39], v[90:91], v[38:39]
	v_pk_mul_f32 v[42:43], v[32:33], v[0:1] op_sel_hi:[1,0]
	v_pk_fma_f32 v[40:41], v[38:39], 0, v[36:37] op_sel_hi:[1,0,1]
	v_pk_fma_f32 v[36:37], v[36:37], 0, v[38:39] op_sel_hi:[1,0,1] neg_lo:[1,0,0] neg_hi:[1,0,0]
	v_pk_mul_f32 v[38:39], v[24:25], v[0:1] op_sel_hi:[1,0]
	v_pk_mul_f32 v[42:43], v[92:93], v[42:43]
	v_pk_mul_f32 v[38:39], v[96:97], v[38:39]
	v_pk_mul_f32 v[46:47], v[26:27], v[0:1] op_sel_hi:[1,0]
	v_pk_fma_f32 v[44:45], v[42:43], 0, v[38:39] op_sel_hi:[1,0,1]
	v_pk_fma_f32 v[38:39], v[38:39], 0, v[42:43] op_sel_hi:[1,0,1] neg_lo:[1,0,0] neg_hi:[1,0,0]
	v_pk_mul_f32 v[42:43], v[18:19], v[0:1] op_sel_hi:[1,0]
	v_pk_mul_f32 v[46:47], v[82:83], v[46:47]
	v_pk_mul_f32 v[42:43], v[86:87], v[42:43]
	v_pk_mul_f32 v[50:51], v[28:29], v[0:1] op_sel_hi:[1,0]
	v_pk_fma_f32 v[48:49], v[46:47], 0, v[42:43] op_sel_hi:[1,0,1]
	v_pk_fma_f32 v[42:43], v[42:43], 0, v[46:47] op_sel_hi:[1,0,1] neg_lo:[1,0,0] neg_hi:[1,0,0]
	v_pk_mul_f32 v[46:47], v[20:21], v[0:1] op_sel_hi:[1,0]
	v_pk_mul_f32 v[50:51], v[84:85], v[50:51]
	v_pk_mul_f32 v[46:47], v[88:89], v[46:47]
	v_lshlrev_b32_e32 v0, 7, v34
	v_pk_fma_f32 v[52:53], v[50:51], 0, v[46:47] op_sel_hi:[1,0,1]
	v_pk_fma_f32 v[46:47], v[46:47], 0, v[50:51] op_sel_hi:[1,0,1] neg_lo:[1,0,0] neg_hi:[1,0,0]
	v_lshl_add_u64 v[50:51], s[0:1], 0, v[0:1]
	v_lshl_add_u64 v[50:51], v[50:51], 0, v[146:147]
	v_cvt_pk_bf16_f32 v36, v36, v37
	v_cvt_pk_bf16_f32 v37, v38, v39
	v_cvt_pk_bf16_f32 v38, v42, v43
	v_cvt_pk_bf16_f32 v39, v46, v47
	global_store_dwordx4 v[50:51], v[36:39], off
	s_nop 1
	v_cvt_pk_bf16_f32 v36, v40, v41
	v_cvt_pk_bf16_f32 v37, v44, v45
	v_cvt_pk_bf16_f32 v38, v48, v49
	v_cvt_pk_bf16_f32 v39, v52, v53
	global_store_dwordx4 v[50:51], v[36:39], off offset:64

; DI u16 f2bf(float a) { return (u16)(pack_bf16(a, 0.f) & 0xffffu); }
;   DI void operator()(const f32x4 (&acc)[2][2][4][2], const Unit& u, int wr, int wc, int fr, int fq) const {
;     ...
;         if (rowbase == 0) { b = t >> 12; pos = t & 4095; } else { b = t >> 8; pos = 4096 + (t & 255); }
;         u16* base = qkv + (size_t)(b * 32 + chunk) * LTOT * 64;
;         if (isV) {
; #pragma unroll
;           for (int bj = 0; bj < 2; ++bj)
; #pragma unroll
;             for (int n = 0; n < 2; ++n)
; #pragma unroll
;               for (int e = 0; e < 4; ++e) {
;                 int d = 32 * bj + 8 * fq + 4 * n + e;
;                 base[(size_t)d * LTOT + pos] = f2bf(acc[ai][bj][m][n][e]);
;               }
;         } else {
;           float ss = 0.f;
; #pragma unroll
;           for (int bj = 0; bj < 2; ++bj)
; #pragma unroll
;             for (int n = 0; n < 2; ++n)
; #pragma unroll
;               for (int e = 0; e < 4; ++e) ss += acc[ai][bj][m][n][e] * acc[ai][bj][m][n][e];
;           ss += __shfl_xor(ss, 16);
;           ss += __shfl_xor(ss, 32);
;           const float rinv = rsqrtf(ss * (1.f / 64.f) + EPSV);
;           float o1[8], o2[8];
; #pragma unroll
;           for (int n = 0; n < 2; ++n) {
;             f32x4 cs0 = (f32x4){1.f, 0.f, 1.f, 0.f}, cs1 = cs0;
;             if (ropeT) { cs0 = csr[m & 1][n][0]; cs1 = csr[m & 1][n][1]; }
; #pragma unroll
;             for (int e = 0; e < 4; ++e) {
;               float x1 = acc[ai][0][m][n][e] * (rinv * qs) * g4[0][n][e];
;               float x2 = acc[ai][1][m][n][e] * (rinv * qs) * g4[1][n][e];
;               float c = (e < 2) ? cs0[2 * e] : cs1[2 * (e - 2)], s = (e < 2) ? cs0[2 * e + 1] : cs1[2 * (e - 2) + 1];
;               o1[n * 4 + e] = x1 * c - x2 * s;
;               o2[n * 4 + e] = x2 * c + x1 * s;
;             }
;           }
;           u16* dst = base + (size_t)pos * 64 + 8 * fq;
;           *(uint4*)(dst) = make_uint4(pack_bf16(o1[0], o1[1]), pack_bf16(o1[2], o1[3]), pack_bf16(o1[4], o1[5]), pack_bf16(o1[6], o1[7]));
;           *(uint4*)(dst + 32) = make_uint4(pack_bf16(o2[0], o2[1]), pack_bf16(o2[2], o2[3]), pack_bf16(o2[4], o2[5]), pack_bf16(o2[6], o2[7]));
.LBB0_869:
	s_add_i32 s0, s15, 0xb0
	s_add_i32 s1, s0, s10
	s_and_b32 s0, s0, 0xf0
	v_or_b32_e32 v0, s0, v150
	s_ashr_i32 s0, s1, 3
	s_andn2_b32 s0, s0, 31
	s_add_i32 s0, s0, s8
	s_mul_hi_i32 s1, s0, 0x88000
	s_mul_i32 s0, s0, 0x88000
	s_add_u32 s0, s88, s0
	v_or_b32_e32 v18, 0x1000, v0
	s_addc_u32 s1, s89, s1
	s_and_b64 vcc, exec, s[4:5]
	s_mov_b64 s[2:3], -1
	s_cbranch_vccnz .LBB0_871
	v_mul_f32_e32 v0, v15, v15
	v_fmac_f32_e32 v0, v14, v14
	v_fmac_f32_e32 v0, v16, v16
	v_fmac_f32_e32 v0, v17, v17
	v_fmac_f32_e32 v0, v10, v10
	v_fmac_f32_e32 v0, v11, v11
	v_fmac_f32_e32 v0, v12, v12
	v_fmac_f32_e32 v0, v13, v13
	v_pk_mul_f32 v[22:23], v[6:7], v[6:7]
	v_pk_mul_f32 v[20:21], v[8:9], v[8:9]
	v_add_f32_e32 v0, v22, v0
	v_add_f32_e32 v0, v23, v0
	v_add_f32_e32 v0, v20, v0
	v_add_f32_e32 v0, v21, v0
	v_pk_mul_f32 v[22:23], v[2:3], v[2:3]
	v_pk_mul_f32 v[20:21], v[4:5], v[4:5]
	v_add_f32_e32 v0, v22, v0
	v_add_f32_e32 v0, v23, v0
	v_add_f32_e32 v0, v20, v0
	v_and_b32_e32 v20, 64, v211
	v_xor_b32_e32 v19, 16, v211
	v_add_u32_e32 v20, 64, v20
	v_cmp_lt_i32_e32 vcc, v19, v20
	v_add_f32_e32 v0, v21, v0
	v_mov_b32_e32 v147, v1
	v_cndmask_b32_e32 v19, v211, v19, vcc
	v_lshlrev_b32_e32 v19, 2, v19
	ds_bpermute_b32 v19, v19, v0
	s_mov_b64 s[2:3], 0
	s_waitcnt lgkmcnt(0)
	v_add_f32_e32 v0, v0, v19
	v_xor_b32_e32 v19, 32, v211
	v_cmp_lt_i32_e32 vcc, v19, v20
	s_nop 1
	v_cndmask_b32_e32 v19, v211, v19, vcc
	v_lshlrev_b32_e32 v19, 2, v19
	ds_bpermute_b32 v19, v19, v0
	s_waitcnt lgkmcnt(0)
	v_add_f32_e32 v0, v0, v19
	v_fmamk_f32 v0, v0, 0x3c800000, v210
	v_mul_f32_e32 v19, 0x4b800000, v0
	v_cmp_gt_f32_e32 vcc, s11, v0
	s_nop 1
	v_cndmask_b32_e32 v0, v0, v19, vcc
	v_rsq_f32_e32 v0, v0
	s_nop 0
	v_mul_f32_e32 v19, 0x45800000, v0
	v_cndmask_b32_e32 v0, v0, v19, vcc
	v_mul_f32_e32 v0, v151, v0
	v_pk_mul_f32 v[20:21], v[6:7], v[0:1] op_sel_hi:[1,0]
	v_pk_mul_f32 v[22:23], v[14:15], v[0:1] op_sel_hi:[1,0]
	v_pk_mul_f32 v[20:21], v[94:95], v[20:21]
	v_pk_mul_f32 v[22:23], v[90:91], v[22:23]
	v_pk_mul_f32 v[26:27], v[16:17], v[0:1] op_sel_hi:[1,0]
	v_pk_fma_f32 v[24:25], v[22:23], 0, v[20:21] op_sel_hi:[1,0,1]
	v_pk_fma_f32 v[20:21], v[20:21], 0, v[22:23] op_sel_hi:[1,0,1] neg_lo:[1,0,0] neg_hi:[1,0,0]
	v_pk_mul_f32 v[22:23], v[8:9], v[0:1] op_sel_hi:[1,0]
	v_pk_mul_f32 v[26:27], v[92:93], v[26:27]
	v_pk_mul_f32 v[22:23], v[96:97], v[22:23]
	v_pk_mul_f32 v[30:31], v[10:11], v[0:1] op_sel_hi:[1,0]
	v_pk_fma_f32 v[28:29], v[26:27], 0, v[22:23] op_sel_hi:[1,0,1]
	v_pk_fma_f32 v[22:23], v[22:23], 0, v[26:27] op_sel_hi:[1,0,1] neg_lo:[1,0,0] neg_hi:[1,0,0]
	v_pk_mul_f32 v[26:27], v[2:3], v[0:1] op_sel_hi:[1,0]
	v_pk_mul_f32 v[30:31], v[82:83], v[30:31]
	v_pk_mul_f32 v[26:27], v[86:87], v[26:27]
	v_pk_mul_f32 v[34:35], v[12:13], v[0:1] op_sel_hi:[1,0]
	v_pk_fma_f32 v[32:33], v[30:31], 0, v[26:27] op_sel_hi:[1,0,1]
	v_pk_fma_f32 v[26:27], v[26:27], 0, v[30:31] op_sel_hi:[1,0,1] neg_lo:[1,0,0] neg_hi:[1,0,0]
	v_pk_mul_f32 v[30:31], v[4:5], v[0:1] op_sel_hi:[1,0]
	v_pk_mul_f32 v[34:35], v[84:85], v[34:35]
	v_pk_mul_f32 v[30:31], v[88:89], v[30:31]
	v_lshlrev_b32_e32 v0, 7, v18
	v_pk_fma_f32 v[36:37], v[34:35], 0, v[30:31] op_sel_hi:[1,0,1]
	v_pk_fma_f32 v[30:31], v[30:31], 0, v[34:35] op_sel_hi:[1,0,1] neg_lo:[1,0,0] neg_hi:[1,0,0]
	v_lshl_add_u64 v[34:35], s[0:1], 0, v[0:1]
	v_lshl_add_u64 v[34:35], v[34:35], 0, v[146:147]
	v_cvt_pk_bf16_f32 v20, v20, v21
	v_cvt_pk_bf16_f32 v21, v22, v23
	v_cvt_pk_bf16_f32 v22, v26, v27
	v_cvt_pk_bf16_f32 v23, v30, v31
	global_store_dwordx4 v[34:35], v[20:23], off
	s_nop 1
	v_cvt_pk_bf16_f32 v20, v24, v25
	v_cvt_pk_bf16_f32 v21, v28, v29
	v_cvt_pk_bf16_f32 v22, v32, v33
	v_cvt_pk_bf16_f32 v23, v36, v37
	global_store_dwordx4 v[34:35], v[20:23], off offset:64
